# P1 in-projection: wave output columns remapped so a wave owns both halves of each 128-byte line; epilogue merges the two half-line stores into full-line stores with DPP row shifts
# baseline (speedup 1.0000x reference)
; #define LAS __attribute__((address_space(3)))
; #define PG8_STAGEA(bufoff, gbase) PG8_STAGE_(bufoff, gbase, voffA)
; #define PG8_STAGEB(bufoff, gbase) PG8_STAGE_(bufoff, gbase, voffB)
; template <int EK, int SK = -1>
; __device__ __forceinline__ void gemm_phase(LAS unsigned char* lds, const bf16_t* A, const bf16_t* Bt, int nM, int N, int K, const EpiArgs& E) {
;     const int tid = threadIdx.x, wid = __builtin_amdgcn_readfirstlane(tid >> 6), lane = tid & 63, wr = wid >> 2, wc = wid & 3, fr = lane & 15, fq = lane >> 4;
;     const int nt = K / BK;
;     SOrder S; S.init(nM, N, (int)gridDim.x, (int)blockIdx.x);
;     LAS float* rtab = (LAS float*)(lds + RTAB_OFF);
;     unsigned voffA[2], voffB[2];
; #pragma unroll
;     for (int i = 0; i < 2; ++i) { int R, C; stage_rc(tid * 16 + i * 8192, R, C); const int Rb = (R & ~31) + perm32(R & 31);
;         voffA[i] = (unsigned)(R * K + C) * 2u; voffB[i] = (unsigned)(Rb * K + C) * 2u; }
;     ...
;     const char* cA = (const char*)A + (size_t)cur.pm * tstep; const char* cB = (const char*)Bt + (size_t)cur.pn * tstep;
;     PG8_STAGEB(PG8_SB(0, 0), cB); PG8_STAGEB(PG8_SB(0, 1), cB + hstep); PG8_STAGEA(PG8_SA(0, 0), cA); PG8_STAGEA(PG8_SA(0, 1), cA + hstep);
;     f32x4 tq[4][4]; bool okq[4];
;     if (EK != EK_RES && EK != EK_FINAL) {
; #pragma unroll
;         for (int j = 0; j < 4; ++j) { Unit uu; okq[j] = S.next((tid >> 8) + 2 * j, uu);
;             if (okq[j]) { const f32x4* sp = (const f32x4*)(E.stIn + (size_t)(uu.pm * BM + (tid & 255)) * 16); tq[j][0] = sp[0]; tq[j][1] = sp[1]; tq[j][2] = sp[2]; tq[j][3] = sp[3]; } }
.LBB0_147:
	s_load_dword s86, s[0:1], 0xb8
	s_andn2_b64 vcc, exec, s[4:5]
	s_cbranch_vccnz .LBB0_206
	v_lshrrev_b32_e32 v3, 1, v0
	v_and_b32_e32 v90, 24, v3
	v_lshrrev_b32_e32 v3, 5, v0
	v_lshlrev_b32_e32 v1, 4, v0
	v_and_b32_e32 v2, 32, v0
	v_and_b32_e32 v3, 4, v3
	v_bfe_u32 v4, v0, 2, 2
	v_bfe_u32 v88, v0, 2, 4
	v_bitop3_b32 v86, v1, v2, 48 bitop3:0x6c
	v_and_b32_e32 v87, 64, v0
	v_or3_b32 v3, v3, v4, v90
	v_lshrrev_b32_e32 v4, 3, v0
	v_or_b32_e32 v89, 0x2000, v1
	v_or_b32_e32 v2, v86, v87
	v_and_or_b32 v5, v4, 48, v88
	v_and_or_b32 v4, v4, 32, v3
	v_lshrrev_b32_e32 v1, 7, v89
	s_waitcnt lgkmcnt(0)
	s_movk_i32 s3, 0x70
	v_lshl_or_b32 v132, v4, 11, v2
	v_and_b32_e32 v233, 0x30000, v132
	v_add_u32_e32 v132, v132, v233
	v_and_or_b32 v4, v1, s3, v88
	s_movk_i32 s3, 0x60
	s_lshr_b32 s52, s54, 6
	v_and_or_b32 v1, v1, s3, v3
	s_lshl_b32 s87, s52, 10
	s_ashr_i32 s3, s2, 31
	s_add_u32 s12, s30, 0xaea0000
	s_addc_u32 s13, s31, 0
	s_ashr_i32 s67, s66, 31
	s_ashr_i32 s69, s68, 31
	s_lshl_b64 s[4:5], s[66:67], 19
	s_lshl_b64 s[6:7], s[68:69], 19
	s_add_u32 s78, s30, s6
	s_addc_u32 s79, s31, s7
	s_add_i32 s67, s87, 0
	s_add_i32 m0, s67, 0x10000
	v_lshl_or_b32 v136, v1, 11, v2
	v_and_b32_e32 v233, 0x30000, v136
	v_add_u32_e32 v136, v136, v233
	global_load_lds_dwordx4 v132, s[78:79]
	s_add_i32 m0, s67, 0x12000
	s_add_u32 s6, s78, 0x10000
	global_load_lds_dwordx4 v136, s[78:79]
	s_addc_u32 s7, s79, 0
	s_add_i32 m0, s67, 0x14000
	v_lshl_or_b32 v130, v5, 11, v2
	global_load_lds_dwordx4 v132, s[6:7]
	s_add_i32 m0, s67, 0x16000
	s_add_u32 s70, s62, s4
	s_addc_u32 s71, s63, s5
	s_add_i32 s69, s67, 0x2000
	global_load_lds_dwordx4 v136, s[6:7]
	s_mov_b32 m0, s67
	s_add_u32 s4, s70, 0x40000
	v_lshl_or_b32 v134, v4, 11, v2
	global_load_lds_dwordx4 v130, s[70:71]
	s_mov_b32 m0, s69
	s_addc_u32 s5, s71, 0
	s_add_i32 s88, s67, 0x4000
	global_load_lds_dwordx4 v134, s[70:71]
	s_mov_b32 m0, s88
	s_add_i32 s89, s67, 0x6000
	global_load_lds_dwordx4 v130, s[4:5]
	s_mov_b32 m0, s89
	s_waitcnt vmcnt(0)
	v_lshrrev_b32_e32 v50, 8, v0
	global_load_lds_dwordx4 v134, s[4:5]
	v_mov_b64_e32 v[2:3], s[2:3]
	v_mad_i64_i32 v[2:3], s[4:5], s86, v50, v[2:3]
	v_mov_b32_e32 v133, 0
	s_mov_b64 s[4:5], 0x200
	v_mov_b32_e32 v137, v133
	v_mov_b32_e32 v131, v133
	v_mov_b32_e32 v135, v133
	v_and_b32_e32 v1, 0xff, v0
	v_cmp_gt_i64_e64 s[4:5], s[4:5], v[2:3]
	s_and_saveexec_b64 s[6:7], s[4:5]
	s_cbranch_execz .LBB0_154
	v_ashrrev_i32_e32 v3, 31, v2
	v_lshrrev_b32_e32 v3, 29, v3
	v_add_u32_e32 v4, v2, v3
	v_and_b32_e32 v3, -8, v4
	v_sub_u32_e32 v3, v2, v3
	v_cmp_lt_i32_e32 vcc, -1, v3
	s_and_saveexec_b64 s[8:9], vcc
	s_xor_b64 s[8:9], exec, s[8:9]
	v_lshlrev_b32_e32 v2, 6, v3
	s_or_saveexec_b64 s[8:9], s[8:9]
	v_ashrrev_i32_e32 v4, 3, v4
	s_xor_b64 exec, exec, s[8:9]
	v_lshl_add_u32 v2, v3, 6, v3
	s_or_b64 exec, exec, s[8:9]
	v_add_u32_e32 v2, v2, v4
	v_ashrrev_i32_e32 v3, 31, v2
	v_lshrrev_b32_e32 v3, 27, v3
	v_add_u32_e32 v3, v2, v3
	v_ashrrev_i32_e32 v4, 5, v3
	v_lshlrev_b32_e32 v4, 2, v4
	v_sub_u32_e32 v5, 64, v4
	v_min_i32_e32 v5, 4, v5
	v_sub_u32_e32 v6, 0, v5
	v_max_i32_e32 v5, v5, v6
	v_cvt_f32_u32_e32 v6, v5
	v_and_b32_e32 v3, 0xffffffe0, v3
	v_sub_u32_e32 v2, v2, v3
	v_sub_u32_e32 v7, 0, v2
	v_rcp_iflag_f32_e32 v6, v6
	v_ashrrev_i32_e32 v3, 31, v2
	v_max_i32_e32 v2, v2, v7
	v_sub_u32_e32 v7, 0, v5
	v_mul_f32_e32 v6, 0x4f7ffffe, v6
	v_cvt_u32_f32_e32 v6, v6
	v_mul_lo_u32 v7, v7, v6
	v_mul_hi_u32 v7, v6, v7
	v_add_u32_e32 v6, v6, v7
	v_mul_hi_u32 v6, v2, v6
	v_mul_lo_u32 v6, v6, v5
	v_sub_u32_e32 v2, v2, v6
	v_sub_u32_e32 v6, v2, v5
	v_cmp_ge_u32_e32 vcc, v2, v5
	s_nop 1
	v_cndmask_b32_e32 v2, v2, v6, vcc
	v_sub_u32_e32 v6, v2, v5
	v_cmp_ge_u32_e32 vcc, v2, v5
	s_nop 1
	v_cndmask_b32_e32 v2, v2, v6, vcc
	v_xor_b32_e32 v2, v2, v3
	v_sub_u32_e32 v2, v2, v3
	v_add_u32_e32 v2, v4, v2
	v_lshl_or_b32 v2, v2, 8, v1
	v_ashrrev_i32_e32 v3, 31, v2
	v_lshlrev_b64 v[2:3], 6, v[2:3]
	v_lshl_add_u64 v[14:15], s[12:13], 0, v[2:3]
	global_load_dwordx4 v[2:5], v[14:15], off offset:48
	global_load_dwordx4 v[10:13], v[14:15], off offset:32
	global_load_dwordx4 v[6:9], v[14:15], off offset:16
	s_nop 0
	global_load_dwordx4 v[14:17], v[14:15], off

; #define PG8_STAGEA(bufoff, gbase) PG8_STAGE_(bufoff, gbase, voffA)
; #define PG8_STAGEB(bufoff, gbase) PG8_STAGE_(bufoff, gbase, voffB)
; #define PG8_WAIT_V(n) asm volatile("s_waitcnt vmcnt(" #n ")" ::: "memory")
; #define PG8_BAR __builtin_amdgcn_s_barrier()
; template <int EK, int SK = -1>
; __device__ __forceinline__ void gemm_phase(LAS unsigned char* lds, const bf16_t* A, const bf16_t* Bt, int nM, int N, int K, const EpiArgs& E) {
;     ...
;     const unsigned ldsw = (unsigned)wid * 1024u;
;     const int aoff = lds_byte(wr * 64 + fr, fq * 8), boff = lds_byte(wc * 32 + fr, fq * 8);
;     ...
;     PG8_WAIT_V(2); PG8_BAR;
;     PG8_STAGEB(PG8_SB(1, 0), cB + kstep); PG8_STAGEA(PG8_SA(1, 0), cA + kstep); PG8_STAGEB(PG8_SB(1, 1), cB + hstep + kstep);
;     PG8_WAIT_V(6); PG8_BAR;
.LBB0_189:
	v_lshlrev_b32_e32 v2, 1, v90
	v_lshlrev_b32_e32 v4, 2, v91
	v_lshl_or_b32 v3, v91, 6, v2
	s_lshl_b32 s5, s4, 13
	v_and_b32_e32 v5, 32, v4
	v_bitop3_b32 v5, v3, s5, v5 bitop3:0xde
	s_lshl_b32 s5, s52, 5
	v_lshlrev_b32_e32 v3, 6, v0
	s_movk_i32 s6, 0x3c0
	s_and_b32 s5, s5, 0x60
	v_and_or_b32 v2, v3, s6, v2
	v_lshlrev_b32_e32 v3, 2, v0
	s_lshl_b32 s6, s5, 7
	v_and_b32_e32 v3, 32, v3
	s_mov_b64 s[10:11], 0x80
	v_bitop3_b32 v152, s6, v2, v3 bitop3:0xf6
	s_add_i32 m0, s67, 0x18000
	v_lshl_add_u64 v[2:3], v[76:77], 0, s[10:11]
	s_waitcnt vmcnt(2)
	s_barrier
	global_load_lds_dwordx4 v[2:3], off
	v_lshl_add_u64 v[2:3], v[74:75], 0, s[10:11]
	s_add_i32 m0, s67, 0x1a000
	s_add_i32 s52, s67, 0x8000
	s_add_i32 s53, s67, 0xa000
	global_load_lds_dwordx4 v[2:3], off
	v_lshl_add_u64 v[2:3], v[72:73], 0, s[10:11]
	s_mov_b32 m0, s52
	s_add_u32 s12, s78, 0x10080
	global_load_lds_dwordx4 v[2:3], off
	v_lshl_add_u64 v[2:3], v[70:71], 0, s[10:11]
	s_mov_b32 m0, s53
	s_addc_u32 s13, s79, 0
	global_load_lds_dwordx4 v[2:3], off
	s_add_i32 m0, s67, 0x1c000
	v_lshl_add_u64 v[2:3], s[12:13], 0, v[132:133]
	global_load_lds_dwordx4 v[2:3], off
	v_lshl_add_u64 v[2:3], s[12:13], 0, v[136:137]
	s_add_i32 m0, s67, 0x1e000
	v_lshl_or_b32 v1, s4, 6, v91
	global_load_lds_dwordx4 v[2:3], off
	s_lshl_b32 s4, s4, 8
	s_add_i32 s4, s4, 0
	s_add_i32 s4, s4, 0x20010
	v_lshlrev_b32_e32 v2, 8, v0
	v_add_u32_e32 v153, s4, v4
	v_and_b32_e32 v2, 0x18000, v2
	v_lshlrev_b32_e32 v4, 11, v88
	v_or3_b32 v2, v86, v2, v4
	s_mov_b64 s[6:7], 0x40080
	v_add_u32_e32 v2, v2, v87
	v_mov_b32_e32 v3, 0
	v_lshl_add_u64 v[138:139], v[2:3], 0, s[6:7]
	v_lshlrev_b32_e32 v2, 4, v89
	v_and_b32_e32 v2, 0x38000, v2
	s_waitcnt vmcnt(6)
	v_or3_b32 v2, v86, v2, v4
	s_cmpk_lt_u32 s54, 0x100
	v_add_u32_e32 v2, v2, v87
	s_mov_b32 s56, 0
	s_cselect_b64 s[12:13], -1, 0
	v_or_b32_e32 v154, s5, v90
	v_lshl_add_u64 v[140:141], v[2:3], 0, s[6:7]
	v_mov_b64_e32 v[142:143], 0x200
	v_mov_b64_e32 v[144:145], 0x1ff
	s_add_i32 s54, 0, 0x10000
	s_add_i32 s55, 0, 0x14000
	v_add_u32_e32 v155, 0, v5
	v_mov_b32_e32 v2, v3
	s_barrier
	s_branch .LBB0_191

; #define PG8_STAGEA(bufoff, gbase) PG8_STAGE_(bufoff, gbase, voffA)
; #define PG8_STAGEB(bufoff, gbase) PG8_STAGE_(bufoff, gbase, voffB)
; #define PG8_LDA(dst, b, h) do { _Pragma("unroll") for (int m = 0; m < 4; ++m) _Pragma("unroll") for (int k = 0; k < 2; ++k) dst[m][k] = *(const LAS bf16x8*)(lds + PG8_SA(b, h) + aoff + m * 2048 + k * 1024); } while (0)
; #define PG8_LDB(dst, b, h) do { _Pragma("unroll") for (int n = 0; n < 2; ++n) _Pragma("unroll") for (int k = 0; k < 2; ++k) dst[n][k] = *(const LAS bf16x8*)(lds + PG8_SB(b, h) + boff + n * 2048 + k * 1024); } while (0)
; #define PG8_MMA(ai, bj, At, Bt_) do { __builtin_amdgcn_s_setprio(1); _Pragma("unroll") for (int m = 0; m < 4; ++m) _Pragma("unroll") for (int n = 0; n < 2; ++n) _Pragma("unroll") for (int k = 0; k < 2; ++k) \
;         acc[ai][bj][m][n] = __builtin_amdgcn_mfma_f32_16x16x32_bf16(Bt_[n][k], At[m][k], acc[ai][bj][m][n], 0, 0, 0); __builtin_amdgcn_s_setprio(0); } while (0)
; #define PG8_WAIT_V(n) asm volatile("s_waitcnt vmcnt(" #n ")" ::: "memory")
; #define PG8_WAIT_L(n) asm volatile("s_waitcnt lgkmcnt(" #n ")" ::: "memory")
; #define PG8_BAR __builtin_amdgcn_s_barrier()
; template <int EK, int SK = -1>
; __device__ __forceinline__ void gemm_phase(LAS unsigned char* lds, const bf16_t* A, const bf16_t* Bt, int nM, int N, int K, const EpiArgs& E) {
;     ...
;         const bool has_next = S.next(ui + 1, nxt);
;         const char* nA = has_next ? (const char*)A + (size_t)nxt.pm * tstep : cA; const char* nB = has_next ? (const char*)Bt + (size_t)nxt.pn * tstep : cB;
;         for (int t = 0; t < nt; t += 2) {
;             const bool last = (t == nt - 2);
;             const char* a1 = cA + (size_t)(t + 1) * kstep;
;             const char* a2 = last ? nA : cA + (size_t)(t + 2) * kstep; const char* b2 = last ? nB : cB + (size_t)(t + 2) * kstep;
;             const char* a3 = a2 + kstep; const char* b3 = b2 + kstep;
;             PG8_LDB(B0, 0, 0); PG8_LDB(B1, 0, 1); PG8_SCHED; PG8_LDA(At, 0, 0); PG8_STAGEA(PG8_SA(1, 1), a1 + hstep);
;             PG8_WAIT_V(8); PG8_WAIT_L(0); PG8_BAR; PG8_MMA(0, 0, At, B0); PG8_MMA(0, 1, At, B1); PG8_BAR; PG8_SCHED;
;             PG8_LDA(At, 0, 1); PG8_STAGEB(PG8_SB(0, 0), b2); PG8_STAGEB(PG8_SB(0, 1), b2 + hstep); PG8_STAGEA(PG8_SA(0, 0), a2);
;             PG8_WAIT_V(8); PG8_WAIT_L(0); PG8_BAR; PG8_MMA(1, 0, At, B0); PG8_MMA(1, 1, At, B1); PG8_BAR; PG8_SCHED;
.LBB0_197:
	s_add_u32 s58, s78, 0x100
	s_addc_u32 s59, s79, 0
	s_ashr_i32 s75, s74, 31
	s_lshl_b64 s[76:77], s[74:75], 19
	s_add_u32 s80, s62, s76
	s_addc_u32 s81, s63, s77
	s_and_b64 s[76:77], s[6:7], exec
	s_cselect_b32 s75, s81, s71
	s_cselect_b32 s90, s80, s70
	s_ashr_i32 s73, s72, 31
	s_lshl_b64 s[76:77], s[72:73], 19
	s_add_u32 s76, s30, s76
	s_addc_u32 s77, s31, s77
	s_and_b64 s[82:83], s[6:7], exec
	s_cselect_b32 s73, s77, s79
	s_cselect_b32 s91, s76, s78
	v_lshl_add_u64 v[146:147], s[70:71], 0, v[138:139]
	v_lshl_add_u64 v[148:149], s[70:71], 0, v[140:141]
	s_mov_b32 s92, -2
	s_mov_b64 s[78:79], 0
	v_add_u32_e32 v150, s54, v152
	ds_read_b128 v[156:159], v150
	ds_read_b128 v[160:163], v150 offset:1024
	ds_read_b128 v[164:167], v150 offset:2048
	ds_read_b128 v[168:171], v150 offset:3072
	v_add_u32_e32 v150, s55, v152
	s_add_u32 s82, s70, s78
	ds_read_b128 v[172:175], v150
	ds_read_b128 v[176:179], v150 offset:1024
	ds_read_b128 v[180:183], v150 offset:2048
	ds_read_b128 v[184:187], v150 offset:3072
	s_addc_u32 s83, s71, s79
	s_add_u32 s82, s82, 0x100
	s_addc_u32 s83, s83, 0
	s_add_u32 s93, s58, s78
	s_addc_u32 s94, s59, s79
	s_cmpk_eq_i32 s78, 0x700
	s_cselect_b32 s85, s75, s83
	s_cselect_b32 s84, s90, s82
	s_cselect_b32 s83, s73, s94
	s_cselect_b32 s82, s91, s93
	v_lshl_add_u64 v[150:151], v[146:147], 0, s[78:79]
	s_add_i32 m0, s67, 0xc000
	ds_read_b128 v[188:191], v155
	ds_read_b128 v[192:195], v155 offset:1024
	ds_read_b128 v[196:199], v155 offset:2048
	ds_read_b128 v[200:203], v155 offset:3072
	ds_read_b128 v[204:207], v155 offset:4096
	ds_read_b128 v[208:211], v155 offset:5120
	ds_read_b128 v[212:215], v155 offset:6144
	ds_read_b128 v[216:219], v155 offset:7168
	global_load_lds_dwordx4 v[150:151], off
	v_lshl_add_u64 v[150:151], v[148:149], 0, s[78:79]
	s_add_i32 m0, s67, 0xe000
	s_nop 0
	global_load_lds_dwordx4 v[150:151], off
	s_waitcnt vmcnt(8)
	s_waitcnt lgkmcnt(0)
	s_barrier
	s_waitcnt lgkmcnt(0)
	v_mfma_f32_16x16x32_bf16 v[110:113], v[156:159], v[188:191], 0
	v_mfma_f32_16x16x32_bf16 v[106:109], v[164:167], v[188:191], 0
	v_mfma_f32_16x16x32_bf16 v[102:105], v[156:159], v[196:199], 0
	v_mfma_f32_16x16x32_bf16 v[98:101], v[164:167], v[196:199], 0
	v_mfma_f32_16x16x32_bf16 v[94:97], v[156:159], v[204:207], 0
	v_mfma_f32_16x16x32_bf16 v[90:93], v[164:167], v[204:207], 0
	v_mfma_f32_16x16x32_bf16 v[86:89], v[156:159], v[212:215], 0
	v_mfma_f32_16x16x32_bf16 v[82:85], v[164:167], v[212:215], 0
	v_mfma_f32_16x16x32_bf16 v[110:113], v[160:163], v[192:195], v[110:113]
	v_mfma_f32_16x16x32_bf16 v[106:109], v[168:171], v[192:195], v[106:109]
	v_mfma_f32_16x16x32_bf16 v[102:105], v[160:163], v[200:203], v[102:105]
	v_mfma_f32_16x16x32_bf16 v[98:101], v[168:171], v[200:203], v[98:101]
	v_mfma_f32_16x16x32_bf16 v[94:97], v[160:163], v[208:211], v[94:97]
	v_mfma_f32_16x16x32_bf16 v[90:93], v[168:171], v[208:211], v[90:93]
	v_mfma_f32_16x16x32_bf16 v[86:89], v[160:163], v[216:219], v[86:89]
	v_mfma_f32_16x16x32_bf16 v[82:85], v[168:171], v[216:219], v[82:85]
	v_mfma_f32_16x16x32_bf16 v[78:81], v[172:175], v[188:191], 0
	v_mfma_f32_16x16x32_bf16 v[74:77], v[180:183], v[188:191], 0
	v_mfma_f32_16x16x32_bf16 v[70:73], v[172:175], v[196:199], 0
	v_mfma_f32_16x16x32_bf16 v[66:69], v[180:183], v[196:199], 0
	v_mfma_f32_16x16x32_bf16 v[62:65], v[172:175], v[204:207], 0
	v_mfma_f32_16x16x32_bf16 v[58:61], v[180:183], v[204:207], 0
	v_mfma_f32_16x16x32_bf16 v[54:57], v[172:175], v[212:215], 0
	v_mfma_f32_16x16x32_bf16 v[50:53], v[180:183], v[212:215], 0
	v_mfma_f32_16x16x32_bf16 v[78:81], v[176:179], v[192:195], v[78:81]
	v_mfma_f32_16x16x32_bf16 v[74:77], v[184:187], v[192:195], v[74:77]
	v_mfma_f32_16x16x32_bf16 v[70:73], v[176:179], v[200:203], v[70:73]
	v_mfma_f32_16x16x32_bf16 v[66:69], v[184:187], v[200:203], v[66:69]
	v_mfma_f32_16x16x32_bf16 v[62:65], v[176:179], v[208:211], v[62:65]
	v_mfma_f32_16x16x32_bf16 v[58:61], v[184:187], v[208:211], v[58:61]
	v_mfma_f32_16x16x32_bf16 v[54:57], v[176:179], v[216:219], v[54:57]
	v_mfma_f32_16x16x32_bf16 v[50:53], v[184:187], v[216:219], v[50:53]
	s_barrier
	s_add_i32 s93, s54, s87
	v_lshl_add_u64 v[150:151], s[82:83], 0, v[132:133]
	s_mov_b32 m0, s93
	ds_read_b128 v[188:191], v155 offset:16384
	ds_read_b128 v[192:195], v155 offset:17408
	ds_read_b128 v[196:199], v155 offset:18432
	ds_read_b128 v[200:203], v155 offset:19456
	ds_read_b128 v[204:207], v155 offset:20480
	ds_read_b128 v[208:211], v155 offset:21504
	ds_read_b128 v[212:215], v155 offset:22528
	ds_read_b128 v[216:219], v155 offset:23552
	global_load_lds_dwordx4 v[150:151], off
	s_add_i32 m0, s93, 0x2000
	s_add_u32 s94, s82, 0x10000
	v_lshl_add_u64 v[220:221], s[82:83], 0, v[136:137]
	s_addc_u32 s95, s83, 0
	s_add_i32 s93, s55, s87
	global_load_lds_dwordx4 v[220:221], off
	v_lshl_add_u64 v[222:223], s[94:95], 0, v[132:133]
	s_mov_b32 m0, s93
	v_lshl_add_u64 v[224:225], s[84:85], 0, v[134:135]
	global_load_lds_dwordx4 v[222:223], off
	v_lshl_add_u64 v[222:223], s[94:95], 0, v[136:137]
	s_add_i32 m0, s93, 0x2000
	s_nop 0
	global_load_lds_dwordx4 v[222:223], off
	v_lshl_add_u64 v[222:223], s[84:85], 0, v[130:131]
	s_mov_b32 m0, s67
	s_nop 0
	global_load_lds_dwordx4 v[222:223], off
	s_mov_b32 m0, s69
	s_nop 0
	global_load_lds_dwordx4 v[224:225], off
	s_waitcnt vmcnt(8)
	s_waitcnt lgkmcnt(0)
	s_barrier
; #define PG8_STAGEA(bufoff, gbase) PG8_STAGE_(bufoff, gbase, voffA)
; #define PG8_LDA(dst, b, h) do { _Pragma("unroll") for (int m = 0; m < 4; ++m) _Pragma("unroll") for (int k = 0; k < 2; ++k) dst[m][k] = *(const LAS bf16x8*)(lds + PG8_SA(b, h) + aoff + m * 2048 + k * 1024); } while (0)
; #define PG8_LDB(dst, b, h) do { _Pragma("unroll") for (int n = 0; n < 2; ++n) _Pragma("unroll") for (int k = 0; k < 2; ++k) dst[n][k] = *(const LAS bf16x8*)(lds + PG8_SB(b, h) + boff + n * 2048 + k * 1024); } while (0)
; #define PG8_MMA(ai, bj, At, Bt_) do { __builtin_amdgcn_s_setprio(1); _Pragma("unroll") for (int m = 0; m < 4; ++m) _Pragma("unroll") for (int n = 0; n < 2; ++n) _Pragma("unroll") for (int k = 0; k < 2; ++k) \
;         acc[ai][bj][m][n] = __builtin_amdgcn_mfma_f32_16x16x32_bf16(Bt_[n][k], At[m][k], acc[ai][bj][m][n], 0, 0, 0); __builtin_amdgcn_s_setprio(0); } while (0)
; #define PG8_WAIT_V(n) asm volatile("s_waitcnt vmcnt(" #n ")" ::: "memory")
; #define PG8_WAIT_L(n) asm volatile("s_waitcnt lgkmcnt(" #n ")" ::: "memory")
; #define PG8_BAR __builtin_amdgcn_s_barrier()
; #define PG8_SCHED __builtin_amdgcn_sched_barrier(0)
; template <int EK, int SK = -1>
; __device__ __forceinline__ void gemm_phase(LAS unsigned char* lds, const bf16_t* A, const bf16_t* Bt, int nM, int N, int K, const EpiArgs& E) {
;     ...
;             PG8_WAIT_V(8); PG8_WAIT_L(0); PG8_BAR; PG8_MMA(1, 0, At, B0); PG8_MMA(1, 1, At, B1); PG8_BAR; PG8_SCHED;
;             PG8_LDB(B0, 1, 0); PG8_LDB(B1, 1, 1); PG8_SCHED; PG8_LDA(At, 1, 0); PG8_STAGEA(PG8_SA(0, 1), a2 + hstep);
;             PG8_WAIT_V(8); PG8_WAIT_L(0); PG8_BAR; PG8_MMA(0, 0, At, B0); PG8_MMA(0, 1, At, B1); PG8_BAR; PG8_SCHED;
	s_waitcnt lgkmcnt(0)
	v_mfma_f32_16x16x32_bf16 v[46:49], v[156:159], v[188:191], 0
	v_mfma_f32_16x16x32_bf16 v[42:45], v[164:167], v[188:191], 0
	v_mfma_f32_16x16x32_bf16 v[38:41], v[156:159], v[196:199], 0
	v_mfma_f32_16x16x32_bf16 v[34:37], v[164:167], v[196:199], 0
	v_mfma_f32_16x16x32_bf16 v[30:33], v[156:159], v[204:207], 0
	v_mfma_f32_16x16x32_bf16 v[26:29], v[164:167], v[204:207], 0
	v_mfma_f32_16x16x32_bf16 v[22:25], v[156:159], v[212:215], 0
	v_mfma_f32_16x16x32_bf16 v[18:21], v[164:167], v[212:215], 0
	v_mfma_f32_16x16x32_bf16 v[46:49], v[160:163], v[192:195], v[46:49]
	v_mfma_f32_16x16x32_bf16 v[42:45], v[168:171], v[192:195], v[42:45]
	v_mfma_f32_16x16x32_bf16 v[38:41], v[160:163], v[200:203], v[38:41]
	v_mfma_f32_16x16x32_bf16 v[34:37], v[168:171], v[200:203], v[34:37]
	v_mfma_f32_16x16x32_bf16 v[30:33], v[160:163], v[208:211], v[30:33]
	v_mfma_f32_16x16x32_bf16 v[26:29], v[168:171], v[208:211], v[26:29]
	v_mfma_f32_16x16x32_bf16 v[22:25], v[160:163], v[216:219], v[22:25]
	v_mfma_f32_16x16x32_bf16 v[18:21], v[168:171], v[216:219], v[18:21]
	v_mfma_f32_16x16x32_bf16 v[14:17], v[172:175], v[188:191], 0
	v_mfma_f32_16x16x32_bf16 v[10:13], v[180:183], v[188:191], 0
	v_mfma_f32_16x16x32_bf16 v[6:9], v[172:175], v[196:199], 0
	v_mfma_f32_16x16x32_bf16 v[2:5], v[180:183], v[196:199], 0
	v_mfma_f32_16x16x32_bf16 v[114:117], v[172:175], v[204:207], 0
	v_mfma_f32_16x16x32_bf16 v[118:121], v[180:183], v[204:207], 0
	v_mfma_f32_16x16x32_bf16 v[122:125], v[172:175], v[212:215], 0
	v_mfma_f32_16x16x32_bf16 v[126:129], v[180:183], v[212:215], 0
	v_mfma_f32_16x16x32_bf16 v[14:17], v[176:179], v[192:195], v[14:17]
	v_mfma_f32_16x16x32_bf16 v[10:13], v[184:187], v[192:195], v[10:13]
	v_mfma_f32_16x16x32_bf16 v[6:9], v[176:179], v[200:203], v[6:9]
	v_mfma_f32_16x16x32_bf16 v[2:5], v[184:187], v[200:203], v[2:5]
	v_mfma_f32_16x16x32_bf16 v[114:117], v[176:179], v[208:211], v[114:117]
	v_mfma_f32_16x16x32_bf16 v[118:121], v[184:187], v[208:211], v[118:121]
	v_mfma_f32_16x16x32_bf16 v[122:125], v[176:179], v[216:219], v[122:125]
	v_mfma_f32_16x16x32_bf16 v[126:129], v[184:187], v[216:219], v[126:129]
	s_barrier
	s_add_i32 s93, 0, 0x18000
	s_add_i32 s94, 0, 0x1c000
	v_add_u32_e32 v168, s93, v152
	v_add_u32_e32 v184, s94, v152
	ds_read_b128 v[156:159], v168
	ds_read_b128 v[160:163], v168 offset:1024
	ds_read_b128 v[164:167], v168 offset:2048
	ds_read_b128 v[168:171], v168 offset:3072
	ds_read_b128 v[172:175], v184
	ds_read_b128 v[176:179], v184 offset:1024
	ds_read_b128 v[180:183], v184 offset:2048
	ds_read_b128 v[184:187], v184 offset:3072
	s_add_u32 s84, s84, 0x40000
	s_addc_u32 s85, s85, 0
	s_mov_b32 m0, s88
	v_lshl_add_u64 v[226:227], s[84:85], 0, v[130:131]
	ds_read_b128 v[188:191], v155 offset:32768
	ds_read_b128 v[192:195], v155 offset:33792
	ds_read_b128 v[196:199], v155 offset:34816
	ds_read_b128 v[200:203], v155 offset:35840
	ds_read_b128 v[204:207], v155 offset:36864
	ds_read_b128 v[208:211], v155 offset:37888
	ds_read_b128 v[212:215], v155 offset:38912
	ds_read_b128 v[216:219], v155 offset:39936
	global_load_lds_dwordx4 v[226:227], off
	v_lshl_add_u64 v[226:227], s[84:85], 0, v[134:135]
	s_mov_b32 m0, s89
	s_nop 0
	global_load_lds_dwordx4 v[226:227], off
	s_waitcnt vmcnt(8)
	s_waitcnt lgkmcnt(0)
	s_barrier
	s_waitcnt lgkmcnt(0)
	v_mfma_f32_16x16x32_bf16 v[110:113], v[156:159], v[188:191], v[110:113]
	v_mfma_f32_16x16x32_bf16 v[106:109], v[164:167], v[188:191], v[106:109]
	v_mfma_f32_16x16x32_bf16 v[102:105], v[156:159], v[196:199], v[102:105]
	v_mfma_f32_16x16x32_bf16 v[98:101], v[164:167], v[196:199], v[98:101]
	v_mfma_f32_16x16x32_bf16 v[94:97], v[156:159], v[204:207], v[94:97]
	v_mfma_f32_16x16x32_bf16 v[90:93], v[164:167], v[204:207], v[90:93]
	v_mfma_f32_16x16x32_bf16 v[86:89], v[156:159], v[212:215], v[86:89]
	v_mfma_f32_16x16x32_bf16 v[82:85], v[164:167], v[212:215], v[82:85]
	v_mfma_f32_16x16x32_bf16 v[110:113], v[160:163], v[192:195], v[110:113]
	v_mfma_f32_16x16x32_bf16 v[106:109], v[168:171], v[192:195], v[106:109]
	v_mfma_f32_16x16x32_bf16 v[102:105], v[160:163], v[200:203], v[102:105]
	v_mfma_f32_16x16x32_bf16 v[98:101], v[168:171], v[200:203], v[98:101]
	v_mfma_f32_16x16x32_bf16 v[94:97], v[160:163], v[208:211], v[94:97]
	v_mfma_f32_16x16x32_bf16 v[90:93], v[168:171], v[208:211], v[90:93]
	v_mfma_f32_16x16x32_bf16 v[86:89], v[160:163], v[216:219], v[86:89]
	v_mfma_f32_16x16x32_bf16 v[82:85], v[168:171], v[216:219], v[82:85]
	v_mfma_f32_16x16x32_bf16 v[78:81], v[172:175], v[188:191], v[78:81]
	v_mfma_f32_16x16x32_bf16 v[74:77], v[180:183], v[188:191], v[74:77]
	v_mfma_f32_16x16x32_bf16 v[70:73], v[172:175], v[196:199], v[70:73]
	v_mfma_f32_16x16x32_bf16 v[66:69], v[180:183], v[196:199], v[66:69]
	v_mfma_f32_16x16x32_bf16 v[62:65], v[172:175], v[204:207], v[62:65]
	v_mfma_f32_16x16x32_bf16 v[58:61], v[180:183], v[204:207], v[58:61]
	v_mfma_f32_16x16x32_bf16 v[54:57], v[172:175], v[212:215], v[54:57]
	v_mfma_f32_16x16x32_bf16 v[50:53], v[180:183], v[212:215], v[50:53]
	v_mfma_f32_16x16x32_bf16 v[78:81], v[176:179], v[192:195], v[78:81]
	v_mfma_f32_16x16x32_bf16 v[74:77], v[184:187], v[192:195], v[74:77]
	v_mfma_f32_16x16x32_bf16 v[70:73], v[176:179], v[200:203], v[70:73]
	v_mfma_f32_16x16x32_bf16 v[66:69], v[184:187], v[200:203], v[66:69]
	v_mfma_f32_16x16x32_bf16 v[62:65], v[176:179], v[208:211], v[62:65]
	v_mfma_f32_16x16x32_bf16 v[58:61], v[184:187], v[208:211], v[58:61]
	v_mfma_f32_16x16x32_bf16 v[54:57], v[176:179], v[216:219], v[54:57]
	v_mfma_f32_16x16x32_bf16 v[50:53], v[184:187], v[216:219], v[50:53]
	s_barrier
; #define PG8_STAGEA(bufoff, gbase) PG8_STAGE_(bufoff, gbase, voffA)
; #define PG8_STAGEB(bufoff, gbase) PG8_STAGE_(bufoff, gbase, voffB)
; #define PG8_LDA(dst, b, h) do { _Pragma("unroll") for (int m = 0; m < 4; ++m) _Pragma("unroll") for (int k = 0; k < 2; ++k) dst[m][k] = *(const LAS bf16x8*)(lds + PG8_SA(b, h) + aoff + m * 2048 + k * 1024); } while (0)
; #define PG8_LDB(dst, b, h) do { _Pragma("unroll") for (int n = 0; n < 2; ++n) _Pragma("unroll") for (int k = 0; k < 2; ++k) dst[n][k] = *(const LAS bf16x8*)(lds + PG8_SB(b, h) + boff + n * 2048 + k * 1024); } while (0)
; #define PG8_MMA(ai, bj, At, Bt_) do { __builtin_amdgcn_s_setprio(1); _Pragma("unroll") for (int m = 0; m < 4; ++m) _Pragma("unroll") for (int n = 0; n < 2; ++n) _Pragma("unroll") for (int k = 0; k < 2; ++k) \
;         acc[ai][bj][m][n] = __builtin_amdgcn_mfma_f32_16x16x32_bf16(Bt_[n][k], At[m][k], acc[ai][bj][m][n], 0, 0, 0); __builtin_amdgcn_s_setprio(0); } while (0)
; #define PG8_WAIT_V(n) asm volatile("s_waitcnt vmcnt(" #n ")" ::: "memory")
; #define PG8_WAIT_L(n) asm volatile("s_waitcnt lgkmcnt(" #n ")" ::: "memory")
; #define PG8_BAR __builtin_amdgcn_s_barrier()
; #define PG8_SCHED __builtin_amdgcn_sched_barrier(0)
; template <int EK, int SK = -1>
; __device__ __forceinline__ void gemm_phase(LAS unsigned char* lds, const bf16_t* A, const bf16_t* Bt, int nM, int N, int K, const EpiArgs& E) {
;     ...
;             PG8_LDB(B0, 0, 0); PG8_LDB(B1, 0, 1); PG8_SCHED; PG8_LDA(At, 0, 0); PG8_STAGEA(PG8_SA(1, 1), a1 + hstep);
;             PG8_WAIT_V(8); PG8_WAIT_L(0); PG8_BAR; PG8_MMA(0, 0, At, B0); PG8_MMA(0, 1, At, B1); PG8_BAR; PG8_SCHED;
;             PG8_LDA(At, 0, 1); PG8_STAGEB(PG8_SB(0, 0), b2); PG8_STAGEB(PG8_SB(0, 1), b2 + hstep); PG8_STAGEA(PG8_SA(0, 0), a2);
;             PG8_WAIT_V(8); PG8_WAIT_L(0); PG8_BAR; PG8_MMA(1, 0, At, B0); PG8_MMA(1, 1, At, B1); PG8_BAR; PG8_SCHED;
;             PG8_LDB(B0, 1, 0); PG8_LDB(B1, 1, 1); PG8_SCHED; PG8_LDA(At, 1, 0); PG8_STAGEA(PG8_SA(0, 1), a2 + hstep);
;             PG8_WAIT_V(8); PG8_WAIT_L(0); PG8_BAR; PG8_MMA(0, 0, At, B0); PG8_MMA(0, 1, At, B1); PG8_BAR; PG8_SCHED;
;             PG8_LDA(At, 1, 1); PG8_STAGEB(PG8_SB(1, 0), b3); PG8_STAGEB(PG8_SB(1, 1), b3 + hstep); PG8_STAGEA(PG8_SA(1, 0), a3);
;             PG8_WAIT_V(8); PG8_WAIT_L(0); PG8_BAR; PG8_MMA(1, 0, At, B0); PG8_MMA(1, 1, At, B1); PG8_BAR; PG8_SCHED;
;         }
	s_add_i32 s84, s93, s87
	v_lshl_add_u64 v[150:151], v[150:151], 0, s[10:11]
	s_mov_b32 m0, s84
	ds_read_b128 v[188:191], v155 offset:49152
	ds_read_b128 v[192:195], v155 offset:50176
	ds_read_b128 v[196:199], v155 offset:51200
	ds_read_b128 v[200:203], v155 offset:52224
	ds_read_b128 v[204:207], v155 offset:53248
	ds_read_b128 v[208:211], v155 offset:54272
	ds_read_b128 v[212:215], v155 offset:55296
	ds_read_b128 v[216:219], v155 offset:56320
	global_load_lds_dwordx4 v[150:151], off
	s_add_i32 m0, s84, 0x2000
	s_add_u32 s82, s82, 0x10080
	v_lshl_add_u64 v[150:151], v[220:221], 0, s[10:11]
	s_addc_u32 s83, s83, 0
	s_add_i32 s84, s94, s87
	global_load_lds_dwordx4 v[150:151], off
	v_lshl_add_u64 v[150:151], s[82:83], 0, v[132:133]
	s_mov_b32 m0, s84
	s_nop 0
	global_load_lds_dwordx4 v[150:151], off
	v_lshl_add_u64 v[150:151], s[82:83], 0, v[136:137]
	s_add_i32 m0, s84, 0x2000
	s_nop 0
	global_load_lds_dwordx4 v[150:151], off
	v_lshl_add_u64 v[150:151], v[222:223], 0, s[10:11]
	s_mov_b32 m0, s52
	s_nop 0
	global_load_lds_dwordx4 v[150:151], off
	v_lshl_add_u64 v[150:151], v[224:225], 0, s[10:11]
	s_mov_b32 m0, s53
	s_nop 0
	global_load_lds_dwordx4 v[150:151], off
	s_waitcnt vmcnt(8)
	s_waitcnt lgkmcnt(0)
	s_barrier
	s_waitcnt lgkmcnt(0)
	v_mfma_f32_16x16x32_bf16 v[46:49], v[156:159], v[188:191], v[46:49]
	v_mfma_f32_16x16x32_bf16 v[42:45], v[164:167], v[188:191], v[42:45]
	v_mfma_f32_16x16x32_bf16 v[38:41], v[156:159], v[196:199], v[38:41]
	v_mfma_f32_16x16x32_bf16 v[34:37], v[164:167], v[196:199], v[34:37]
	v_mfma_f32_16x16x32_bf16 v[30:33], v[156:159], v[204:207], v[30:33]
	v_mfma_f32_16x16x32_bf16 v[26:29], v[164:167], v[204:207], v[26:29]
	v_mfma_f32_16x16x32_bf16 v[22:25], v[156:159], v[212:215], v[22:25]
	v_mfma_f32_16x16x32_bf16 v[18:21], v[164:167], v[212:215], v[18:21]
	v_mfma_f32_16x16x32_bf16 v[46:49], v[160:163], v[192:195], v[46:49]
	v_mfma_f32_16x16x32_bf16 v[42:45], v[168:171], v[192:195], v[42:45]
	v_mfma_f32_16x16x32_bf16 v[38:41], v[160:163], v[200:203], v[38:41]
	v_mfma_f32_16x16x32_bf16 v[34:37], v[168:171], v[200:203], v[34:37]
	v_mfma_f32_16x16x32_bf16 v[30:33], v[160:163], v[208:211], v[30:33]
	v_mfma_f32_16x16x32_bf16 v[26:29], v[168:171], v[208:211], v[26:29]
	v_mfma_f32_16x16x32_bf16 v[22:25], v[160:163], v[216:219], v[22:25]
	v_mfma_f32_16x16x32_bf16 v[18:21], v[168:171], v[216:219], v[18:21]
	v_mfma_f32_16x16x32_bf16 v[14:17], v[172:175], v[188:191], v[14:17]
	v_mfma_f32_16x16x32_bf16 v[10:13], v[180:183], v[188:191], v[10:13]
	v_mfma_f32_16x16x32_bf16 v[6:9], v[172:175], v[196:199], v[6:9]
	v_mfma_f32_16x16x32_bf16 v[2:5], v[180:183], v[196:199], v[2:5]
	v_mfma_f32_16x16x32_bf16 v[114:117], v[172:175], v[204:207], v[114:117]
	v_mfma_f32_16x16x32_bf16 v[118:121], v[180:183], v[204:207], v[118:121]
	v_mfma_f32_16x16x32_bf16 v[122:125], v[172:175], v[212:215], v[122:125]
	v_mfma_f32_16x16x32_bf16 v[126:129], v[180:183], v[212:215], v[126:129]
	v_mfma_f32_16x16x32_bf16 v[14:17], v[176:179], v[192:195], v[14:17]
	v_mfma_f32_16x16x32_bf16 v[10:13], v[184:187], v[192:195], v[10:13]
	v_mfma_f32_16x16x32_bf16 v[6:9], v[176:179], v[200:203], v[6:9]
	v_mfma_f32_16x16x32_bf16 v[2:5], v[184:187], v[200:203], v[2:5]
	v_mfma_f32_16x16x32_bf16 v[114:117], v[176:179], v[208:211], v[114:117]
	v_mfma_f32_16x16x32_bf16 v[118:121], v[184:187], v[208:211], v[118:121]
	v_mfma_f32_16x16x32_bf16 v[122:125], v[176:179], v[216:219], v[122:125]
	v_mfma_f32_16x16x32_bf16 v[126:129], v[184:187], v[216:219], v[126:129]
	s_barrier
	s_add_i32 s92, s92, 2
	s_add_u32 s78, s78, 0x100
	s_addc_u32 s79, s79, 0
	s_cmp_gt_u32 s92, 13
	s_cbranch_scc0 .LBB0_198
	s_branch .Lmy_kexit_0
.LBB0_198:
	v_add_u32_e32 v150, s54, v152
	ds_read_b128 v[156:159], v150
	ds_read_b128 v[160:163], v150 offset:1024
	ds_read_b128 v[164:167], v150 offset:2048
	ds_read_b128 v[168:171], v150 offset:3072
	v_add_u32_e32 v150, s55, v152
	s_add_u32 s82, s70, s78
	ds_read_b128 v[172:175], v150
	ds_read_b128 v[176:179], v150 offset:1024
	ds_read_b128 v[180:183], v150 offset:2048
	ds_read_b128 v[184:187], v150 offset:3072
	s_addc_u32 s83, s71, s79
	s_add_u32 s82, s82, 0x100
	s_addc_u32 s83, s83, 0
	s_add_u32 s93, s58, s78
	s_addc_u32 s94, s59, s79
	s_cmpk_eq_i32 s78, 0x700
	s_cselect_b32 s85, s75, s83
	s_cselect_b32 s84, s90, s82
	s_cselect_b32 s83, s73, s94
	s_cselect_b32 s82, s91, s93
	v_lshl_add_u64 v[150:151], v[146:147], 0, s[78:79]
	s_add_i32 m0, s67, 0xc000
	ds_read_b128 v[188:191], v155
	ds_read_b128 v[192:195], v155 offset:1024
	ds_read_b128 v[196:199], v155 offset:2048
	ds_read_b128 v[200:203], v155 offset:3072
	ds_read_b128 v[204:207], v155 offset:4096
	ds_read_b128 v[208:211], v155 offset:5120
	ds_read_b128 v[212:215], v155 offset:6144
	ds_read_b128 v[216:219], v155 offset:7168
	global_load_lds_dwordx4 v[150:151], off
	v_lshl_add_u64 v[150:151], v[148:149], 0, s[78:79]
	s_add_i32 m0, s67, 0xe000
	s_nop 0
	global_load_lds_dwordx4 v[150:151], off
	s_waitcnt vmcnt(8)
	s_waitcnt lgkmcnt(0)
	s_barrier
; #define PG8_STAGEA(bufoff, gbase) PG8_STAGE_(bufoff, gbase, voffA)
; #define PG8_STAGEB(bufoff, gbase) PG8_STAGE_(bufoff, gbase, voffB)
; #define PG8_LDA(dst, b, h) do { _Pragma("unroll") for (int m = 0; m < 4; ++m) _Pragma("unroll") for (int k = 0; k < 2; ++k) dst[m][k] = *(const LAS bf16x8*)(lds + PG8_SA(b, h) + aoff + m * 2048 + k * 1024); } while (0)
; #define PG8_MMA(ai, bj, At, Bt_) do { __builtin_amdgcn_s_setprio(1); _Pragma("unroll") for (int m = 0; m < 4; ++m) _Pragma("unroll") for (int n = 0; n < 2; ++n) _Pragma("unroll") for (int k = 0; k < 2; ++k) \
;         acc[ai][bj][m][n] = __builtin_amdgcn_mfma_f32_16x16x32_bf16(Bt_[n][k], At[m][k], acc[ai][bj][m][n], 0, 0, 0); __builtin_amdgcn_s_setprio(0); } while (0)
; #define PG8_WAIT_V(n) asm volatile("s_waitcnt vmcnt(" #n ")" ::: "memory")
; #define PG8_WAIT_L(n) asm volatile("s_waitcnt lgkmcnt(" #n ")" ::: "memory")
; #define PG8_BAR __builtin_amdgcn_s_barrier()
; #define PG8_SCHED __builtin_amdgcn_sched_barrier(0)
; template <int EK, int SK = -1>
; __device__ __forceinline__ void gemm_phase(LAS unsigned char* lds, const bf16_t* A, const bf16_t* Bt, int nM, int N, int K, const EpiArgs& E) {
;     ...
;             PG8_WAIT_V(8); PG8_WAIT_L(0); PG8_BAR; PG8_MMA(0, 0, At, B0); PG8_MMA(0, 1, At, B1); PG8_BAR; PG8_SCHED;
;             PG8_LDA(At, 0, 1); PG8_STAGEB(PG8_SB(0, 0), b2); PG8_STAGEB(PG8_SB(0, 1), b2 + hstep); PG8_STAGEA(PG8_SA(0, 0), a2);
;             PG8_WAIT_V(8); PG8_WAIT_L(0); PG8_BAR; PG8_MMA(1, 0, At, B0); PG8_MMA(1, 1, At, B1); PG8_BAR; PG8_SCHED;
	s_waitcnt lgkmcnt(0)
	v_mfma_f32_16x16x32_bf16 v[110:113], v[156:159], v[188:191], v[110:113]
	v_mfma_f32_16x16x32_bf16 v[106:109], v[164:167], v[188:191], v[106:109]
	v_mfma_f32_16x16x32_bf16 v[102:105], v[156:159], v[196:199], v[102:105]
	v_mfma_f32_16x16x32_bf16 v[98:101], v[164:167], v[196:199], v[98:101]
	v_mfma_f32_16x16x32_bf16 v[94:97], v[156:159], v[204:207], v[94:97]
	v_mfma_f32_16x16x32_bf16 v[90:93], v[164:167], v[204:207], v[90:93]
	v_mfma_f32_16x16x32_bf16 v[86:89], v[156:159], v[212:215], v[86:89]
	v_mfma_f32_16x16x32_bf16 v[82:85], v[164:167], v[212:215], v[82:85]
	v_mfma_f32_16x16x32_bf16 v[110:113], v[160:163], v[192:195], v[110:113]
	v_mfma_f32_16x16x32_bf16 v[106:109], v[168:171], v[192:195], v[106:109]
	v_mfma_f32_16x16x32_bf16 v[102:105], v[160:163], v[200:203], v[102:105]
	v_mfma_f32_16x16x32_bf16 v[98:101], v[168:171], v[200:203], v[98:101]
	v_mfma_f32_16x16x32_bf16 v[94:97], v[160:163], v[208:211], v[94:97]
	v_mfma_f32_16x16x32_bf16 v[90:93], v[168:171], v[208:211], v[90:93]
	v_mfma_f32_16x16x32_bf16 v[86:89], v[160:163], v[216:219], v[86:89]
	v_mfma_f32_16x16x32_bf16 v[82:85], v[168:171], v[216:219], v[82:85]
	v_mfma_f32_16x16x32_bf16 v[78:81], v[172:175], v[188:191], v[78:81]
	v_mfma_f32_16x16x32_bf16 v[74:77], v[180:183], v[188:191], v[74:77]
	v_mfma_f32_16x16x32_bf16 v[70:73], v[172:175], v[196:199], v[70:73]
	v_mfma_f32_16x16x32_bf16 v[66:69], v[180:183], v[196:199], v[66:69]
	v_mfma_f32_16x16x32_bf16 v[62:65], v[172:175], v[204:207], v[62:65]
	v_mfma_f32_16x16x32_bf16 v[58:61], v[180:183], v[204:207], v[58:61]
	v_mfma_f32_16x16x32_bf16 v[54:57], v[172:175], v[212:215], v[54:57]
	v_mfma_f32_16x16x32_bf16 v[50:53], v[180:183], v[212:215], v[50:53]
	v_mfma_f32_16x16x32_bf16 v[78:81], v[176:179], v[192:195], v[78:81]
	v_mfma_f32_16x16x32_bf16 v[74:77], v[184:187], v[192:195], v[74:77]
	v_mfma_f32_16x16x32_bf16 v[70:73], v[176:179], v[200:203], v[70:73]
	v_mfma_f32_16x16x32_bf16 v[66:69], v[184:187], v[200:203], v[66:69]
	v_mfma_f32_16x16x32_bf16 v[62:65], v[176:179], v[208:211], v[62:65]
	v_mfma_f32_16x16x32_bf16 v[58:61], v[184:187], v[208:211], v[58:61]
	v_mfma_f32_16x16x32_bf16 v[54:57], v[176:179], v[216:219], v[54:57]
	v_mfma_f32_16x16x32_bf16 v[50:53], v[184:187], v[216:219], v[50:53]
	s_barrier
	s_add_i32 s93, s54, s87
	v_lshl_add_u64 v[150:151], s[82:83], 0, v[132:133]
	s_mov_b32 m0, s93
	ds_read_b128 v[188:191], v155 offset:16384
	ds_read_b128 v[192:195], v155 offset:17408
	ds_read_b128 v[196:199], v155 offset:18432
	ds_read_b128 v[200:203], v155 offset:19456
	ds_read_b128 v[204:207], v155 offset:20480
	ds_read_b128 v[208:211], v155 offset:21504
	ds_read_b128 v[212:215], v155 offset:22528
	ds_read_b128 v[216:219], v155 offset:23552
	global_load_lds_dwordx4 v[150:151], off
	s_add_i32 m0, s93, 0x2000
	s_add_u32 s94, s82, 0x10000
	v_lshl_add_u64 v[220:221], s[82:83], 0, v[136:137]
	s_addc_u32 s95, s83, 0
	s_add_i32 s93, s55, s87
	global_load_lds_dwordx4 v[220:221], off
	v_lshl_add_u64 v[222:223], s[94:95], 0, v[132:133]
	s_mov_b32 m0, s93
	v_lshl_add_u64 v[224:225], s[84:85], 0, v[134:135]
	global_load_lds_dwordx4 v[222:223], off
	v_lshl_add_u64 v[222:223], s[94:95], 0, v[136:137]
	s_add_i32 m0, s93, 0x2000
	s_nop 0
	global_load_lds_dwordx4 v[222:223], off
	v_lshl_add_u64 v[222:223], s[84:85], 0, v[130:131]
	s_mov_b32 m0, s67
	s_nop 0
	global_load_lds_dwordx4 v[222:223], off
	s_mov_b32 m0, s69
	s_nop 0
	global_load_lds_dwordx4 v[224:225], off
	s_waitcnt vmcnt(8)
	s_waitcnt lgkmcnt(0)
	s_barrier
	s_waitcnt lgkmcnt(0)
	v_mfma_f32_16x16x32_bf16 v[46:49], v[156:159], v[188:191], v[46:49]
	v_mfma_f32_16x16x32_bf16 v[42:45], v[164:167], v[188:191], v[42:45]
	v_mfma_f32_16x16x32_bf16 v[38:41], v[156:159], v[196:199], v[38:41]
	v_mfma_f32_16x16x32_bf16 v[34:37], v[164:167], v[196:199], v[34:37]
	v_mfma_f32_16x16x32_bf16 v[30:33], v[156:159], v[204:207], v[30:33]
	v_mfma_f32_16x16x32_bf16 v[26:29], v[164:167], v[204:207], v[26:29]
	v_mfma_f32_16x16x32_bf16 v[22:25], v[156:159], v[212:215], v[22:25]
	v_mfma_f32_16x16x32_bf16 v[18:21], v[164:167], v[212:215], v[18:21]
	v_mfma_f32_16x16x32_bf16 v[46:49], v[160:163], v[192:195], v[46:49]
	v_mfma_f32_16x16x32_bf16 v[42:45], v[168:171], v[192:195], v[42:45]
	v_mfma_f32_16x16x32_bf16 v[38:41], v[160:163], v[200:203], v[38:41]
	v_mfma_f32_16x16x32_bf16 v[34:37], v[168:171], v[200:203], v[34:37]
	v_mfma_f32_16x16x32_bf16 v[30:33], v[160:163], v[208:211], v[30:33]
	v_mfma_f32_16x16x32_bf16 v[26:29], v[168:171], v[208:211], v[26:29]
	v_mfma_f32_16x16x32_bf16 v[22:25], v[160:163], v[216:219], v[22:25]
	v_mfma_f32_16x16x32_bf16 v[18:21], v[168:171], v[216:219], v[18:21]
	v_mfma_f32_16x16x32_bf16 v[14:17], v[172:175], v[188:191], v[14:17]
	v_mfma_f32_16x16x32_bf16 v[10:13], v[180:183], v[188:191], v[10:13]
	v_mfma_f32_16x16x32_bf16 v[6:9], v[172:175], v[196:199], v[6:9]
	v_mfma_f32_16x16x32_bf16 v[2:5], v[180:183], v[196:199], v[2:5]
	v_mfma_f32_16x16x32_bf16 v[114:117], v[172:175], v[204:207], v[114:117]
	v_mfma_f32_16x16x32_bf16 v[118:121], v[180:183], v[204:207], v[118:121]
	v_mfma_f32_16x16x32_bf16 v[122:125], v[172:175], v[212:215], v[122:125]
	v_mfma_f32_16x16x32_bf16 v[126:129], v[180:183], v[212:215], v[126:129]
	v_mfma_f32_16x16x32_bf16 v[14:17], v[176:179], v[192:195], v[14:17]
	v_mfma_f32_16x16x32_bf16 v[10:13], v[184:187], v[192:195], v[10:13]
	v_mfma_f32_16x16x32_bf16 v[6:9], v[176:179], v[200:203], v[6:9]
	v_mfma_f32_16x16x32_bf16 v[2:5], v[184:187], v[200:203], v[2:5]
	v_mfma_f32_16x16x32_bf16 v[114:117], v[176:179], v[208:211], v[114:117]
	v_mfma_f32_16x16x32_bf16 v[118:121], v[184:187], v[208:211], v[118:121]
	v_mfma_f32_16x16x32_bf16 v[122:125], v[176:179], v[216:219], v[122:125]
	v_mfma_f32_16x16x32_bf16 v[126:129], v[184:187], v[216:219], v[126:129]
	s_barrier
; #define PG8_STAGEA(bufoff, gbase) PG8_STAGE_(bufoff, gbase, voffA)
; #define PG8_STAGEB(bufoff, gbase) PG8_STAGE_(bufoff, gbase, voffB)
; #define PG8_LDA(dst, b, h) do { _Pragma("unroll") for (int m = 0; m < 4; ++m) _Pragma("unroll") for (int k = 0; k < 2; ++k) dst[m][k] = *(const LAS bf16x8*)(lds + PG8_SA(b, h) + aoff + m * 2048 + k * 1024); } while (0)
; #define PG8_LDB(dst, b, h) do { _Pragma("unroll") for (int n = 0; n < 2; ++n) _Pragma("unroll") for (int k = 0; k < 2; ++k) dst[n][k] = *(const LAS bf16x8*)(lds + PG8_SB(b, h) + boff + n * 2048 + k * 1024); } while (0)
; #define PG8_MMA(ai, bj, At, Bt_) do { __builtin_amdgcn_s_setprio(1); _Pragma("unroll") for (int m = 0; m < 4; ++m) _Pragma("unroll") for (int n = 0; n < 2; ++n) _Pragma("unroll") for (int k = 0; k < 2; ++k) \
;         acc[ai][bj][m][n] = __builtin_amdgcn_mfma_f32_16x16x32_bf16(Bt_[n][k], At[m][k], acc[ai][bj][m][n], 0, 0, 0); __builtin_amdgcn_s_setprio(0); } while (0)
; #define PG8_WAIT_V(n) asm volatile("s_waitcnt vmcnt(" #n ")" ::: "memory")
; #define PG8_WAIT_L(n) asm volatile("s_waitcnt lgkmcnt(" #n ")" ::: "memory")
; #define PG8_BAR __builtin_amdgcn_s_barrier()
; #define PG8_SCHED __builtin_amdgcn_sched_barrier(0)
; template <int EK, int SK = -1>
; __device__ __forceinline__ void gemm_phase(LAS unsigned char* lds, const bf16_t* A, const bf16_t* Bt, int nM, int N, int K, const EpiArgs& E) {
;     ...
;             PG8_LDB(B0, 1, 0); PG8_LDB(B1, 1, 1); PG8_SCHED; PG8_LDA(At, 1, 0); PG8_STAGEA(PG8_SA(0, 1), a2 + hstep);
;             PG8_WAIT_V(8); PG8_WAIT_L(0); PG8_BAR; PG8_MMA(0, 0, At, B0); PG8_MMA(0, 1, At, B1); PG8_BAR; PG8_SCHED;
;             PG8_LDA(At, 1, 1); PG8_STAGEB(PG8_SB(1, 0), b3); PG8_STAGEB(PG8_SB(1, 1), b3 + hstep); PG8_STAGEA(PG8_SA(1, 0), a3);
;             PG8_WAIT_V(8); PG8_WAIT_L(0); PG8_BAR; PG8_MMA(1, 0, At, B0); PG8_MMA(1, 1, At, B1); PG8_BAR; PG8_SCHED;
;         }
	s_add_i32 s93, 0, 0x18000
	s_add_i32 s94, 0, 0x1c000
	v_add_u32_e32 v168, s93, v152
	v_add_u32_e32 v184, s94, v152
	ds_read_b128 v[156:159], v168
	ds_read_b128 v[160:163], v168 offset:1024
	ds_read_b128 v[164:167], v168 offset:2048
	ds_read_b128 v[168:171], v168 offset:3072
	ds_read_b128 v[172:175], v184
	ds_read_b128 v[176:179], v184 offset:1024
	ds_read_b128 v[180:183], v184 offset:2048
	ds_read_b128 v[184:187], v184 offset:3072
	s_add_u32 s84, s84, 0x40000
	s_addc_u32 s85, s85, 0
	s_mov_b32 m0, s88
	v_lshl_add_u64 v[226:227], s[84:85], 0, v[130:131]
	ds_read_b128 v[188:191], v155 offset:32768
	ds_read_b128 v[192:195], v155 offset:33792
	ds_read_b128 v[196:199], v155 offset:34816
	ds_read_b128 v[200:203], v155 offset:35840
	ds_read_b128 v[204:207], v155 offset:36864
	ds_read_b128 v[208:211], v155 offset:37888
	ds_read_b128 v[212:215], v155 offset:38912
	ds_read_b128 v[216:219], v155 offset:39936
	global_load_lds_dwordx4 v[226:227], off
	v_lshl_add_u64 v[226:227], s[84:85], 0, v[134:135]
	s_mov_b32 m0, s89
	s_nop 0
	global_load_lds_dwordx4 v[226:227], off
	s_waitcnt vmcnt(8)
	s_waitcnt lgkmcnt(0)
	s_barrier
	s_waitcnt lgkmcnt(0)
	v_mfma_f32_16x16x32_bf16 v[110:113], v[156:159], v[188:191], v[110:113]
	v_mfma_f32_16x16x32_bf16 v[106:109], v[164:167], v[188:191], v[106:109]
	v_mfma_f32_16x16x32_bf16 v[102:105], v[156:159], v[196:199], v[102:105]
	v_mfma_f32_16x16x32_bf16 v[98:101], v[164:167], v[196:199], v[98:101]
	v_mfma_f32_16x16x32_bf16 v[94:97], v[156:159], v[204:207], v[94:97]
	v_mfma_f32_16x16x32_bf16 v[90:93], v[164:167], v[204:207], v[90:93]
	v_mfma_f32_16x16x32_bf16 v[86:89], v[156:159], v[212:215], v[86:89]
	v_mfma_f32_16x16x32_bf16 v[82:85], v[164:167], v[212:215], v[82:85]
	v_mfma_f32_16x16x32_bf16 v[110:113], v[160:163], v[192:195], v[110:113]
	v_mfma_f32_16x16x32_bf16 v[106:109], v[168:171], v[192:195], v[106:109]
	v_mfma_f32_16x16x32_bf16 v[102:105], v[160:163], v[200:203], v[102:105]
	v_mfma_f32_16x16x32_bf16 v[98:101], v[168:171], v[200:203], v[98:101]
	v_mfma_f32_16x16x32_bf16 v[94:97], v[160:163], v[208:211], v[94:97]
	v_mfma_f32_16x16x32_bf16 v[90:93], v[168:171], v[208:211], v[90:93]
	v_mfma_f32_16x16x32_bf16 v[86:89], v[160:163], v[216:219], v[86:89]
	v_mfma_f32_16x16x32_bf16 v[82:85], v[168:171], v[216:219], v[82:85]
	v_mfma_f32_16x16x32_bf16 v[78:81], v[172:175], v[188:191], v[78:81]
	v_mfma_f32_16x16x32_bf16 v[74:77], v[180:183], v[188:191], v[74:77]
	v_mfma_f32_16x16x32_bf16 v[70:73], v[172:175], v[196:199], v[70:73]
	v_mfma_f32_16x16x32_bf16 v[66:69], v[180:183], v[196:199], v[66:69]
	v_mfma_f32_16x16x32_bf16 v[62:65], v[172:175], v[204:207], v[62:65]
	v_mfma_f32_16x16x32_bf16 v[58:61], v[180:183], v[204:207], v[58:61]
	v_mfma_f32_16x16x32_bf16 v[54:57], v[172:175], v[212:215], v[54:57]
	v_mfma_f32_16x16x32_bf16 v[50:53], v[180:183], v[212:215], v[50:53]
	v_mfma_f32_16x16x32_bf16 v[78:81], v[176:179], v[192:195], v[78:81]
	v_mfma_f32_16x16x32_bf16 v[74:77], v[184:187], v[192:195], v[74:77]
	v_mfma_f32_16x16x32_bf16 v[70:73], v[176:179], v[200:203], v[70:73]
	v_mfma_f32_16x16x32_bf16 v[66:69], v[184:187], v[200:203], v[66:69]
	v_mfma_f32_16x16x32_bf16 v[62:65], v[176:179], v[208:211], v[62:65]
	v_mfma_f32_16x16x32_bf16 v[58:61], v[184:187], v[208:211], v[58:61]
	v_mfma_f32_16x16x32_bf16 v[54:57], v[176:179], v[216:219], v[54:57]
	v_mfma_f32_16x16x32_bf16 v[50:53], v[184:187], v[216:219], v[50:53]
	s_barrier
	s_add_i32 s84, s93, s87
	v_lshl_add_u64 v[150:151], v[150:151], 0, s[10:11]
	s_mov_b32 m0, s84
	ds_read_b128 v[188:191], v155 offset:49152
	ds_read_b128 v[192:195], v155 offset:50176
	ds_read_b128 v[196:199], v155 offset:51200
	ds_read_b128 v[200:203], v155 offset:52224
	ds_read_b128 v[204:207], v155 offset:53248
	ds_read_b128 v[208:211], v155 offset:54272
	ds_read_b128 v[212:215], v155 offset:55296
	ds_read_b128 v[216:219], v155 offset:56320
	global_load_lds_dwordx4 v[150:151], off
	s_add_i32 m0, s84, 0x2000
	s_add_u32 s82, s82, 0x10080
	v_lshl_add_u64 v[150:151], v[220:221], 0, s[10:11]
	s_addc_u32 s83, s83, 0
	s_add_i32 s84, s94, s87
	global_load_lds_dwordx4 v[150:151], off
	v_lshl_add_u64 v[150:151], s[82:83], 0, v[132:133]
	s_mov_b32 m0, s84
	s_nop 0
	global_load_lds_dwordx4 v[150:151], off
	v_lshl_add_u64 v[150:151], s[82:83], 0, v[136:137]
	s_add_i32 m0, s84, 0x2000
	s_nop 0
	global_load_lds_dwordx4 v[150:151], off
	v_lshl_add_u64 v[150:151], v[222:223], 0, s[10:11]
	s_mov_b32 m0, s52
	s_nop 0
	global_load_lds_dwordx4 v[150:151], off
	v_lshl_add_u64 v[150:151], v[224:225], 0, s[10:11]
	s_mov_b32 m0, s53
	s_nop 0
	global_load_lds_dwordx4 v[150:151], off
	s_waitcnt vmcnt(8)
	s_waitcnt lgkmcnt(0)
	s_barrier
	s_waitcnt lgkmcnt(0)
	v_mfma_f32_16x16x32_bf16 v[46:49], v[156:159], v[188:191], v[46:49]
	v_mfma_f32_16x16x32_bf16 v[42:45], v[164:167], v[188:191], v[42:45]
	v_mfma_f32_16x16x32_bf16 v[38:41], v[156:159], v[196:199], v[38:41]
	v_mfma_f32_16x16x32_bf16 v[34:37], v[164:167], v[196:199], v[34:37]
	v_mfma_f32_16x16x32_bf16 v[30:33], v[156:159], v[204:207], v[30:33]
	v_mfma_f32_16x16x32_bf16 v[26:29], v[164:167], v[204:207], v[26:29]
	v_mfma_f32_16x16x32_bf16 v[22:25], v[156:159], v[212:215], v[22:25]
	v_mfma_f32_16x16x32_bf16 v[18:21], v[164:167], v[212:215], v[18:21]
	v_mfma_f32_16x16x32_bf16 v[46:49], v[160:163], v[192:195], v[46:49]
	v_mfma_f32_16x16x32_bf16 v[42:45], v[168:171], v[192:195], v[42:45]
	v_mfma_f32_16x16x32_bf16 v[38:41], v[160:163], v[200:203], v[38:41]
	v_mfma_f32_16x16x32_bf16 v[34:37], v[168:171], v[200:203], v[34:37]
	v_mfma_f32_16x16x32_bf16 v[30:33], v[160:163], v[208:211], v[30:33]
	v_mfma_f32_16x16x32_bf16 v[26:29], v[168:171], v[208:211], v[26:29]
	v_mfma_f32_16x16x32_bf16 v[22:25], v[160:163], v[216:219], v[22:25]
	v_mfma_f32_16x16x32_bf16 v[18:21], v[168:171], v[216:219], v[18:21]
	v_mfma_f32_16x16x32_bf16 v[14:17], v[172:175], v[188:191], v[14:17]
	v_mfma_f32_16x16x32_bf16 v[10:13], v[180:183], v[188:191], v[10:13]
	v_mfma_f32_16x16x32_bf16 v[6:9], v[172:175], v[196:199], v[6:9]
	v_mfma_f32_16x16x32_bf16 v[2:5], v[180:183], v[196:199], v[2:5]
	v_mfma_f32_16x16x32_bf16 v[114:117], v[172:175], v[204:207], v[114:117]
	v_mfma_f32_16x16x32_bf16 v[118:121], v[180:183], v[204:207], v[118:121]
	v_mfma_f32_16x16x32_bf16 v[122:125], v[172:175], v[212:215], v[122:125]
	v_mfma_f32_16x16x32_bf16 v[126:129], v[180:183], v[212:215], v[126:129]
	v_mfma_f32_16x16x32_bf16 v[14:17], v[176:179], v[192:195], v[14:17]
	v_mfma_f32_16x16x32_bf16 v[10:13], v[184:187], v[192:195], v[10:13]
	v_mfma_f32_16x16x32_bf16 v[6:9], v[176:179], v[200:203], v[6:9]
	v_mfma_f32_16x16x32_bf16 v[2:5], v[184:187], v[200:203], v[2:5]
	v_mfma_f32_16x16x32_bf16 v[114:117], v[176:179], v[208:211], v[114:117]
	v_mfma_f32_16x16x32_bf16 v[118:121], v[184:187], v[208:211], v[118:121]
	v_mfma_f32_16x16x32_bf16 v[122:125], v[176:179], v[216:219], v[122:125]
	v_mfma_f32_16x16x32_bf16 v[126:129], v[184:187], v[216:219], v[126:129]
	s_barrier
	s_add_i32 s92, s92, 2
	s_add_u32 s78, s78, 0x100
	s_addc_u32 s79, s79, 0
	s_cmp_gt_u32 s92, 13
	s_cbranch_scc0 .LBB0_198

; __device__ __forceinline__ u32x2 pack4(f32x4 v) { u32x2 w; w.x = cvt_pk_bf16(v[0], v[1]); w.y = cvt_pk_bf16(v[2], v[3]); return w; }
; template <int EK>
; __device__ __forceinline__ void epi_tile(const f32x4 (&acc)[2][2][4][2], const Unit& u, int wr, int wc, int fr, int fq, const EpiArgs& E, const LAS float* rt) {
;     const int rowb = u.pm * BM + wr * 64 + fr;
;     float rr[2][4];
;     if (EK != EK_RES) {
; #pragma unroll
;         for (int ai = 0; ai < 2; ++ai)
; #pragma unroll
;             for (int m = 0; m < 4; ++m) rr[ai][m] = rt[ai * HALF + wr * 64 + m * 16 + fr];
;     }
; #pragma unroll
;     for (int ai = 0; ai < 2; ++ai) {
; #pragma unroll
;         for (int m = 0; m < 4; ++m) {
;             const int row = rowb + ai * HALF + m * 16;
;             if (EK == EK_SCALE) {
;                 const float r = rr[ai][m];
; #pragma unroll
;                 for (int bj = 0; bj < 2; ++bj) { const int col = u.pn * BM + bj * HALF + wc * 32 + fq * 8;
;                     const u32x2 lo = pack4(acc[ai][bj][m][0] * r), hi = pack4(acc[ai][bj][m][1] * r);
;                     *(u32x4*)(E.ob + (size_t)row * E.ldb + col) = (u32x4){lo.x, lo.y, hi.x, hi.y}; }
.LBB0_201:
	v_bfe_u32 v232, v0, 3, 1
	v_mul_u32_u24_e32 v244, 0x7fc0, v232
	v_sub_u32_e32 v246, 0x8000, v244
	v_sub_u32_e32 v244, 0, v244
	v_sub_u32_e32 v245, 0, v232
	v_mov_b32_e32 v247, 0
	v_lshl_add_u32 v146, s56, 10, v153
	ds_read2_b32 v[160:161], v146 offset1:16
	ds_read2_b32 v[162:163], v146 offset0:32 offset1:48
	ds_read2_b32 v[150:151], v146 offset0:128 offset1:144
	ds_read2_b32 v[146:147], v146 offset0:160 offset1:176
	v_lshl_add_u32 v164, s66, 8, v1
	s_waitcnt lgkmcnt(0)
	v_pk_mul_f32 v[158:159], v[112:113], v[160:161] op_sel_hi:[1,0]
	v_pk_mul_f32 v[156:157], v[110:111], v[160:161] op_sel_hi:[1,0]
	v_lshl_or_b32 v148, s68, 8, v154
	v_bfe_u32 v232, v0, 6, 2
	v_lshl_add_u32 v148, v232, 5, v148
	v_ashrrev_i32_e32 v165, 31, v164
	v_cvt_pk_bf16_f32 v156, v156, v157
	v_cvt_pk_bf16_f32 v157, v158, v159
	v_pk_mul_f32 v[166:167], v[108:109], v[160:161] op_sel_hi:[1,0]
	v_pk_mul_f32 v[158:159], v[106:107], v[160:161] op_sel_hi:[1,0]
	v_ashrrev_i32_e32 v149, 31, v148
	v_cvt_pk_bf16_f32 v158, v158, v159
	v_cvt_pk_bf16_f32 v159, v166, v167
	v_lshlrev_b64 v[166:167], 12, v[164:165]
	v_lshl_add_u64 v[166:167], s[64:65], 0, v[166:167]
	v_lshlrev_b64 v[168:169], 1, v[148:149]
	v_lshl_add_u64 v[148:149], v[166:167], 0, v[168:169]
	v_mov_b32_e32 v232, v156
	v_mov_b32_e32 v233, v157
	v_mov_b32_e32 v234, v158
	v_mov_b32_e32 v235, v159
	v_pk_mul_f32 v[166:167], v[76:77], v[160:161] op_sel_hi:[1,0]
	s_add_u32 s78, s58, 0xffffff00
	v_pk_mul_f32 v[158:159], v[80:81], v[160:161] op_sel_hi:[1,0]
	v_pk_mul_f32 v[156:157], v[78:79], v[160:161] op_sel_hi:[1,0]
	s_addc_u32 s79, s59, -1
	v_cvt_pk_bf16_f32 v156, v156, v157
	v_cvt_pk_bf16_f32 v157, v158, v159
	v_pk_mul_f32 v[158:159], v[74:75], v[160:161] op_sel_hi:[1,0]
	v_mov_b32_e32 v160, v161
	v_cvt_pk_bf16_f32 v158, v158, v159
	v_cvt_pk_bf16_f32 v159, v166, v167
	v_or_b32_e32 v166, 16, v164
	v_ashrrev_i32_e32 v167, 31, v166
	s_nop 1
	v_mov_b32_e32 v236, v156
	v_mov_b32_e32 v237, v157
	v_mov_b32_e32 v238, v158
	v_mov_b32_e32 v239, v159
	v_mov_b32_dpp v236, v232 row_shl:8 row_mask:0xf bank_mask:0x3
	v_mov_b32_dpp v237, v233 row_shl:8 row_mask:0xf bank_mask:0x3
	v_mov_b32_dpp v238, v234 row_shl:8 row_mask:0xf bank_mask:0x3
	v_mov_b32_dpp v239, v235 row_shl:8 row_mask:0xf bank_mask:0x3
	v_mov_b32_dpp v232, v156 row_shr:8 row_mask:0xf bank_mask:0xc
	v_mov_b32_dpp v233, v157 row_shr:8 row_mask:0xf bank_mask:0xc
	v_mov_b32_dpp v234, v158 row_shr:8 row_mask:0xf bank_mask:0xc
	v_mov_b32_dpp v235, v159 row_shr:8 row_mask:0xf bank_mask:0xc
	v_lshl_add_u64 v[240:241], v[148:149], 0, v[244:245]
	v_lshl_add_u64 v[242:243], v[148:149], 0, v[246:247]
	global_store_dwordx4 v[240:241], v[232:235], off
	global_store_dwordx4 v[242:243], v[236:239], off
	v_lshlrev_b64 v[166:167], 12, v[166:167]
	v_lshl_add_u64 v[166:167], s[64:65], 0, v[166:167]
	v_pk_mul_f32 v[158:159], v[104:105], v[160:161] op_sel_hi:[1,0]
	v_pk_mul_f32 v[156:157], v[102:103], v[160:161] op_sel_hi:[1,0]
	v_pk_mul_f32 v[170:171], v[100:101], v[160:161] op_sel_hi:[1,0]
	v_cvt_pk_bf16_f32 v156, v156, v157
	v_cvt_pk_bf16_f32 v157, v158, v159
	v_pk_mul_f32 v[158:159], v[98:99], v[160:161] op_sel_hi:[1,0]
	v_lshl_add_u64 v[166:167], v[166:167], 0, v[168:169]
	v_cvt_pk_bf16_f32 v158, v158, v159
	v_cvt_pk_bf16_f32 v159, v170, v171
	v_mov_b32_e32 v232, v156
	v_mov_b32_e32 v233, v157
	v_mov_b32_e32 v234, v158
	v_mov_b32_e32 v235, v159
	v_pk_mul_f32 v[170:171], v[68:69], v[160:161] op_sel_hi:[1,0]
	s_mov_b64 s[58:59], 0x80000
	v_pk_mul_f32 v[158:159], v[72:73], v[160:161] op_sel_hi:[1,0]
	v_pk_mul_f32 v[156:157], v[70:71], v[160:161] op_sel_hi:[1,0]
	s_nop 0
	v_cvt_pk_bf16_f32 v156, v156, v157
	v_cvt_pk_bf16_f32 v157, v158, v159
	v_pk_mul_f32 v[158:159], v[66:67], v[160:161] op_sel_hi:[1,0]
	v_or_b32_e32 v160, 32, v164
	v_cvt_pk_bf16_f32 v158, v158, v159
	v_cvt_pk_bf16_f32 v159, v170, v171
	v_ashrrev_i32_e32 v161, 31, v160
	s_nop 1
	v_mov_b32_e32 v236, v156
	v_mov_b32_e32 v237, v157
	v_mov_b32_e32 v238, v158
	v_mov_b32_e32 v239, v159
	v_mov_b32_dpp v236, v232 row_shl:8 row_mask:0xf bank_mask:0x3
	v_mov_b32_dpp v237, v233 row_shl:8 row_mask:0xf bank_mask:0x3
	v_mov_b32_dpp v238, v234 row_shl:8 row_mask:0xf bank_mask:0x3
	v_mov_b32_dpp v239, v235 row_shl:8 row_mask:0xf bank_mask:0x3
	v_mov_b32_dpp v232, v156 row_shr:8 row_mask:0xf bank_mask:0xc
	v_mov_b32_dpp v233, v157 row_shr:8 row_mask:0xf bank_mask:0xc
	v_mov_b32_dpp v234, v158 row_shr:8 row_mask:0xf bank_mask:0xc
	v_mov_b32_dpp v235, v159 row_shr:8 row_mask:0xf bank_mask:0xc
	v_lshl_add_u64 v[240:241], v[166:167], 0, v[244:245]
	v_lshl_add_u64 v[242:243], v[166:167], 0, v[246:247]
	global_store_dwordx4 v[240:241], v[232:235], off
	global_store_dwordx4 v[242:243], v[236:239], off
	v_lshlrev_b64 v[160:161], 12, v[160:161]
	v_lshl_add_u64 v[160:161], s[64:65], 0, v[160:161]
	v_pk_mul_f32 v[158:159], v[96:97], v[162:163] op_sel_hi:[1,0]
	v_pk_mul_f32 v[156:157], v[94:95], v[162:163] op_sel_hi:[1,0]
	v_pk_mul_f32 v[166:167], v[92:93], v[162:163] op_sel_hi:[1,0]
	v_cvt_pk_bf16_f32 v156, v156, v157
	v_cvt_pk_bf16_f32 v157, v158, v159
	v_pk_mul_f32 v[158:159], v[90:91], v[162:163] op_sel_hi:[1,0]
	v_lshl_add_u64 v[160:161], v[160:161], 0, v[168:169]
	v_cvt_pk_bf16_f32 v158, v158, v159
	v_cvt_pk_bf16_f32 v159, v166, v167
	v_mov_b32_e32 v232, v156
	v_mov_b32_e32 v233, v157
	v_mov_b32_e32 v234, v158
	v_mov_b32_e32 v235, v159
	v_pk_mul_f32 v[166:167], v[60:61], v[162:163] op_sel_hi:[1,0]
	s_nop 0
	v_pk_mul_f32 v[158:159], v[64:65], v[162:163] op_sel_hi:[1,0]
	v_pk_mul_f32 v[156:157], v[62:63], v[162:163] op_sel_hi:[1,0]
	s_nop 0
	v_cvt_pk_bf16_f32 v156, v156, v157
	v_cvt_pk_bf16_f32 v157, v158, v159
; __device__ __forceinline__ u32x2 pack4(f32x4 v) { u32x2 w; w.x = cvt_pk_bf16(v[0], v[1]); w.y = cvt_pk_bf16(v[2], v[3]); return w; }
; template <int EK>
; __device__ __forceinline__ void epi_tile(const f32x4 (&acc)[2][2][4][2], const Unit& u, int wr, int wc, int fr, int fq, const EpiArgs& E, const LAS float* rt) {
;     const int rowb = u.pm * BM + wr * 64 + fr;
;     float rr[2][4];
;     if (EK != EK_RES) {
; #pragma unroll
;         for (int ai = 0; ai < 2; ++ai)
; #pragma unroll
;             for (int m = 0; m < 4; ++m) rr[ai][m] = rt[ai * HALF + wr * 64 + m * 16 + fr];
;     }
; #pragma unroll
;     for (int ai = 0; ai < 2; ++ai) {
; #pragma unroll
;         for (int m = 0; m < 4; ++m) {
;             const int row = rowb + ai * HALF + m * 16;
;             if (EK == EK_SCALE) {
;                 const float r = rr[ai][m];
; #pragma unroll
;                 for (int bj = 0; bj < 2; ++bj) { const int col = u.pn * BM + bj * HALF + wc * 32 + fq * 8;
;                     const u32x2 lo = pack4(acc[ai][bj][m][0] * r), hi = pack4(acc[ai][bj][m][1] * r);
;                     *(u32x4*)(E.ob + (size_t)row * E.ldb + col) = (u32x4){lo.x, lo.y, hi.x, hi.y}; }
	v_pk_mul_f32 v[158:159], v[58:59], v[162:163] op_sel_hi:[1,0]
	v_mov_b32_e32 v162, v163
	v_cvt_pk_bf16_f32 v158, v158, v159
	v_cvt_pk_bf16_f32 v159, v166, v167
	s_nop 1
	v_mov_b32_e32 v236, v156
	v_mov_b32_e32 v237, v157
	v_mov_b32_e32 v238, v158
	v_mov_b32_e32 v239, v159
	v_mov_b32_dpp v236, v232 row_shl:8 row_mask:0xf bank_mask:0x3
	v_mov_b32_dpp v237, v233 row_shl:8 row_mask:0xf bank_mask:0x3
	v_mov_b32_dpp v238, v234 row_shl:8 row_mask:0xf bank_mask:0x3
	v_mov_b32_dpp v239, v235 row_shl:8 row_mask:0xf bank_mask:0x3
	v_mov_b32_dpp v232, v156 row_shr:8 row_mask:0xf bank_mask:0xc
	v_mov_b32_dpp v233, v157 row_shr:8 row_mask:0xf bank_mask:0xc
	v_mov_b32_dpp v234, v158 row_shr:8 row_mask:0xf bank_mask:0xc
	v_mov_b32_dpp v235, v159 row_shr:8 row_mask:0xf bank_mask:0xc
	v_lshl_add_u64 v[240:241], v[160:161], 0, v[244:245]
	v_lshl_add_u64 v[242:243], v[160:161], 0, v[246:247]
	global_store_dwordx4 v[240:241], v[232:235], off
	global_store_dwordx4 v[242:243], v[236:239], off
	v_or_b32_e32 v160, 48, v164
	v_ashrrev_i32_e32 v161, 31, v160
	v_pk_mul_f32 v[158:159], v[88:89], v[162:163] op_sel_hi:[1,0]
	v_pk_mul_f32 v[156:157], v[86:87], v[162:163] op_sel_hi:[1,0]
	v_lshlrev_b64 v[160:161], 12, v[160:161]
	v_cvt_pk_bf16_f32 v156, v156, v157
	v_cvt_pk_bf16_f32 v157, v158, v159
	v_pk_mul_f32 v[158:159], v[82:83], v[162:163] op_sel_hi:[1,0]
	v_lshl_add_u64 v[160:161], s[64:65], 0, v[160:161]
	v_pk_mul_f32 v[164:165], v[84:85], v[162:163] op_sel_hi:[1,0]
	v_cvt_pk_bf16_f32 v158, v158, v159
	v_lshl_add_u64 v[160:161], v[160:161], 0, v[168:169]
	v_cvt_pk_bf16_f32 v159, v164, v165
	v_mov_b32_e32 v232, v156
	v_mov_b32_e32 v233, v157
	v_mov_b32_e32 v234, v158
	v_mov_b32_e32 v235, v159
	v_pk_mul_f32 v[164:165], v[52:53], v[162:163] op_sel_hi:[1,0]
	s_nop 0
	v_pk_mul_f32 v[158:159], v[56:57], v[162:163] op_sel_hi:[1,0]
	v_pk_mul_f32 v[156:157], v[54:55], v[162:163] op_sel_hi:[1,0]
	s_nop 0
	v_cvt_pk_bf16_f32 v156, v156, v157
	v_cvt_pk_bf16_f32 v157, v158, v159
	v_pk_mul_f32 v[158:159], v[50:51], v[162:163] op_sel_hi:[1,0]
	s_nop 0
	v_cvt_pk_bf16_f32 v158, v158, v159
	v_cvt_pk_bf16_f32 v159, v164, v165
	s_nop 1
	v_mov_b32_e32 v236, v156
	v_mov_b32_e32 v237, v157
	v_mov_b32_e32 v238, v158
	v_mov_b32_e32 v239, v159
	v_mov_b32_dpp v236, v232 row_shl:8 row_mask:0xf bank_mask:0x3
	v_mov_b32_dpp v237, v233 row_shl:8 row_mask:0xf bank_mask:0x3
	v_mov_b32_dpp v238, v234 row_shl:8 row_mask:0xf bank_mask:0x3
	v_mov_b32_dpp v239, v235 row_shl:8 row_mask:0xf bank_mask:0x3
	v_mov_b32_dpp v232, v156 row_shr:8 row_mask:0xf bank_mask:0xc
	v_mov_b32_dpp v233, v157 row_shr:8 row_mask:0xf bank_mask:0xc
	v_mov_b32_dpp v234, v158 row_shr:8 row_mask:0xf bank_mask:0xc
	v_mov_b32_dpp v235, v159 row_shr:8 row_mask:0xf bank_mask:0xc
	v_lshl_add_u64 v[240:241], v[160:161], 0, v[244:245]
	v_lshl_add_u64 v[242:243], v[160:161], 0, v[246:247]
	global_store_dwordx4 v[240:241], v[232:235], off
	global_store_dwordx4 v[242:243], v[236:239], off
	v_pk_mul_f32 v[160:161], v[44:45], v[150:151] op_sel_hi:[1,0]
	s_nop 0
	v_pk_mul_f32 v[158:159], v[48:49], v[150:151] op_sel_hi:[1,0]
	v_pk_mul_f32 v[156:157], v[46:47], v[150:151] op_sel_hi:[1,0]
	s_nop 0
	v_cvt_pk_bf16_f32 v156, v156, v157
	v_cvt_pk_bf16_f32 v157, v158, v159
	v_pk_mul_f32 v[158:159], v[42:43], v[150:151] op_sel_hi:[1,0]
	s_nop 0
	v_cvt_pk_bf16_f32 v158, v158, v159
	v_cvt_pk_bf16_f32 v159, v160, v161
	v_lshl_add_u64 v[160:161], v[148:149], 0, s[58:59]
	s_mov_b32 s58, 0x80000
	v_add_co_u32_e32 v162, vcc, s58, v148
	s_mov_b64 s[58:59], 0x90000
	s_nop 0
	v_addc_co_u32_e32 v163, vcc, 0, v149, vcc
	v_mov_b32_e32 v232, v156
	v_mov_b32_e32 v233, v157
	v_mov_b32_e32 v234, v158
	v_mov_b32_e32 v235, v159
	v_pk_mul_f32 v[162:163], v[12:13], v[150:151] op_sel_hi:[1,0]
	s_nop 0
	v_pk_mul_f32 v[158:159], v[16:17], v[150:151] op_sel_hi:[1,0]
	v_pk_mul_f32 v[156:157], v[14:15], v[150:151] op_sel_hi:[1,0]
	s_nop 0
	v_cvt_pk_bf16_f32 v156, v156, v157
	v_cvt_pk_bf16_f32 v157, v158, v159
	v_pk_mul_f32 v[158:159], v[10:11], v[150:151] op_sel_hi:[1,0]
	v_mov_b32_e32 v150, v151
	v_cvt_pk_bf16_f32 v158, v158, v159
	v_cvt_pk_bf16_f32 v159, v162, v163
	s_nop 1
	v_mov_b32_e32 v236, v156
	v_mov_b32_e32 v237, v157
	v_mov_b32_e32 v238, v158
	v_mov_b32_e32 v239, v159
	v_mov_b32_dpp v236, v232 row_shl:8 row_mask:0xf bank_mask:0x3
	v_mov_b32_dpp v237, v233 row_shl:8 row_mask:0xf bank_mask:0x3
	v_mov_b32_dpp v238, v234 row_shl:8 row_mask:0xf bank_mask:0x3
	v_mov_b32_dpp v239, v235 row_shl:8 row_mask:0xf bank_mask:0x3
	v_mov_b32_dpp v232, v156 row_shr:8 row_mask:0xf bank_mask:0xc
	v_mov_b32_dpp v233, v157 row_shr:8 row_mask:0xf bank_mask:0xc
	v_mov_b32_dpp v234, v158 row_shr:8 row_mask:0xf bank_mask:0xc
	v_mov_b32_dpp v235, v159 row_shr:8 row_mask:0xf bank_mask:0xc
	v_lshl_add_u64 v[240:241], v[160:161], 0, v[244:245]
	v_lshl_add_u64 v[242:243], v[160:161], 0, v[246:247]
	global_store_dwordx4 v[240:241], v[232:235], off
	global_store_dwordx4 v[242:243], v[236:239], off
	v_pk_mul_f32 v[160:161], v[36:37], v[150:151] op_sel_hi:[1,0]
	s_nop 0
	v_pk_mul_f32 v[158:159], v[40:41], v[150:151] op_sel_hi:[1,0]
	v_pk_mul_f32 v[156:157], v[38:39], v[150:151] op_sel_hi:[1,0]
	s_nop 0
	v_cvt_pk_bf16_f32 v156, v156, v157
	v_cvt_pk_bf16_f32 v157, v158, v159
	v_pk_mul_f32 v[158:159], v[34:35], v[150:151] op_sel_hi:[1,0]
	s_nop 0
	v_cvt_pk_bf16_f32 v158, v158, v159
	v_cvt_pk_bf16_f32 v159, v160, v161
	v_lshl_add_u64 v[160:161], v[148:149], 0, s[58:59]
	s_mov_b32 s58, 0x90000
	v_add_co_u32_e32 v162, vcc, s58, v148
; __device__ __forceinline__ u32x2 pack4(f32x4 v) { u32x2 w; w.x = cvt_pk_bf16(v[0], v[1]); w.y = cvt_pk_bf16(v[2], v[3]); return w; }
; template <int EK>
; __device__ __forceinline__ void epi_tile(const f32x4 (&acc)[2][2][4][2], const Unit& u, int wr, int wc, int fr, int fq, const EpiArgs& E, const LAS float* rt) {
;     const int rowb = u.pm * BM + wr * 64 + fr;
;     float rr[2][4];
;     if (EK != EK_RES) {
; #pragma unroll
;         for (int ai = 0; ai < 2; ++ai)
; #pragma unroll
;             for (int m = 0; m < 4; ++m) rr[ai][m] = rt[ai * HALF + wr * 64 + m * 16 + fr];
;     }
; #pragma unroll
;     for (int ai = 0; ai < 2; ++ai) {
; #pragma unroll
;         for (int m = 0; m < 4; ++m) {
;             const int row = rowb + ai * HALF + m * 16;
;             if (EK == EK_SCALE) {
;                 const float r = rr[ai][m];
; #pragma unroll
;                 for (int bj = 0; bj < 2; ++bj) { const int col = u.pn * BM + bj * HALF + wc * 32 + fq * 8;
;                     const u32x2 lo = pack4(acc[ai][bj][m][0] * r), hi = pack4(acc[ai][bj][m][1] * r);
;                     *(u32x4*)(E.ob + (size_t)row * E.ldb + col) = (u32x4){lo.x, lo.y, hi.x, hi.y}; }
	s_mov_b64 s[58:59], 0xa0000
	s_nop 0
	v_addc_co_u32_e32 v163, vcc, 0, v149, vcc
	v_mov_b32_e32 v232, v156
	v_mov_b32_e32 v233, v157
	v_mov_b32_e32 v234, v158
	v_mov_b32_e32 v235, v159
	v_pk_mul_f32 v[162:163], v[4:5], v[150:151] op_sel_hi:[1,0]
	s_nop 0
	v_pk_mul_f32 v[156:157], v[6:7], v[150:151] op_sel_hi:[1,0]
	v_pk_mul_f32 v[158:159], v[8:9], v[150:151] op_sel_hi:[1,0]
	v_cvt_pk_bf16_f32 v156, v156, v157
	v_pk_mul_f32 v[150:151], v[2:3], v[150:151] op_sel_hi:[1,0]
	v_cvt_pk_bf16_f32 v157, v158, v159
	v_cvt_pk_bf16_f32 v159, v162, v163
	s_nop 0
	v_cvt_pk_bf16_f32 v158, v150, v151
	s_nop 1
	v_mov_b32_e32 v236, v156
	v_mov_b32_e32 v237, v157
	v_mov_b32_e32 v238, v158
	v_mov_b32_e32 v239, v159
	v_mov_b32_dpp v236, v232 row_shl:8 row_mask:0xf bank_mask:0x3
	v_mov_b32_dpp v237, v233 row_shl:8 row_mask:0xf bank_mask:0x3
	v_mov_b32_dpp v238, v234 row_shl:8 row_mask:0xf bank_mask:0x3
	v_mov_b32_dpp v239, v235 row_shl:8 row_mask:0xf bank_mask:0x3
	v_mov_b32_dpp v232, v156 row_shr:8 row_mask:0xf bank_mask:0xc
	v_mov_b32_dpp v233, v157 row_shr:8 row_mask:0xf bank_mask:0xc
	v_mov_b32_dpp v234, v158 row_shr:8 row_mask:0xf bank_mask:0xc
	v_mov_b32_dpp v235, v159 row_shr:8 row_mask:0xf bank_mask:0xc
	v_lshl_add_u64 v[240:241], v[160:161], 0, v[244:245]
	v_lshl_add_u64 v[242:243], v[160:161], 0, v[246:247]
	global_store_dwordx4 v[240:241], v[232:235], off
	global_store_dwordx4 v[242:243], v[236:239], off
	v_pk_mul_f32 v[150:151], v[32:33], v[146:147] op_sel_hi:[1,0]
	s_nop 0
	v_pk_mul_f32 v[156:157], v[30:31], v[146:147] op_sel_hi:[1,0]
	v_pk_mul_f32 v[158:159], v[26:27], v[146:147] op_sel_hi:[1,0]
	v_cvt_pk_bf16_f32 v156, v156, v157
	v_cvt_pk_bf16_f32 v157, v150, v151
	v_pk_mul_f32 v[150:151], v[28:29], v[146:147] op_sel_hi:[1,0]
	v_cvt_pk_bf16_f32 v158, v158, v159
	s_nop 0
	v_cvt_pk_bf16_f32 v159, v150, v151
	v_lshl_add_u64 v[150:151], v[148:149], 0, s[58:59]
	s_mov_b32 s58, 0xa0000
	v_add_co_u32_e32 v160, vcc, s58, v148
	s_mov_b64 s[58:59], 0xb0000
	s_nop 0
	v_addc_co_u32_e32 v161, vcc, 0, v149, vcc
	v_mov_b32_e32 v232, v156
	v_mov_b32_e32 v233, v157
	v_mov_b32_e32 v234, v158
	v_mov_b32_e32 v235, v159
	v_pk_mul_f32 v[160:161], v[120:121], v[146:147] op_sel_hi:[1,0]
	s_nop 0
	v_pk_mul_f32 v[158:159], v[116:117], v[146:147] op_sel_hi:[1,0]
	v_pk_mul_f32 v[156:157], v[114:115], v[146:147] op_sel_hi:[1,0]
	s_nop 0
	v_cvt_pk_bf16_f32 v156, v156, v157
	v_cvt_pk_bf16_f32 v157, v158, v159
	v_pk_mul_f32 v[158:159], v[118:119], v[146:147] op_sel_hi:[1,0]
	s_nop 0
	v_cvt_pk_bf16_f32 v158, v158, v159
	v_cvt_pk_bf16_f32 v159, v160, v161
	s_nop 1
	v_mov_b32_e32 v236, v156
	v_mov_b32_e32 v237, v157
	v_mov_b32_e32 v238, v158
	v_mov_b32_e32 v239, v159
	v_mov_b32_dpp v236, v232 row_shl:8 row_mask:0xf bank_mask:0x3
	v_mov_b32_dpp v237, v233 row_shl:8 row_mask:0xf bank_mask:0x3
	v_mov_b32_dpp v238, v234 row_shl:8 row_mask:0xf bank_mask:0x3
	v_mov_b32_dpp v239, v235 row_shl:8 row_mask:0xf bank_mask:0x3
	v_mov_b32_dpp v232, v156 row_shr:8 row_mask:0xf bank_mask:0xc
	v_mov_b32_dpp v233, v157 row_shr:8 row_mask:0xf bank_mask:0xc
	v_mov_b32_dpp v234, v158 row_shr:8 row_mask:0xf bank_mask:0xc
	v_mov_b32_dpp v235, v159 row_shr:8 row_mask:0xf bank_mask:0xc
	v_lshl_add_u64 v[240:241], v[150:151], 0, v[244:245]
	v_lshl_add_u64 v[242:243], v[150:151], 0, v[246:247]
	global_store_dwordx4 v[240:241], v[232:235], off
	global_store_dwordx4 v[242:243], v[236:239], off
	v_mov_b32_e32 v150, v147
	v_pk_mul_f32 v[146:147], v[24:25], v[150:151] op_sel_hi:[1,0]
	v_pk_mul_f32 v[156:157], v[22:23], v[150:151] op_sel_hi:[1,0]
	v_pk_mul_f32 v[158:159], v[18:19], v[150:151] op_sel_hi:[1,0]
	v_cvt_pk_bf16_f32 v156, v156, v157
	v_cvt_pk_bf16_f32 v157, v146, v147
	v_pk_mul_f32 v[146:147], v[20:21], v[150:151] op_sel_hi:[1,0]
	v_lshl_add_u64 v[160:161], v[148:149], 0, s[58:59]
	s_mov_b32 s58, 0xb0000
	v_cvt_pk_bf16_f32 v158, v158, v159
	v_cvt_pk_bf16_f32 v159, v146, v147
	v_add_co_u32_e32 v146, vcc, s58, v148
	s_nop 1
	v_addc_co_u32_e32 v147, vcc, 0, v149, vcc
	v_mov_b32_e32 v232, v156
	v_mov_b32_e32 v233, v157
	v_mov_b32_e32 v234, v158
	v_mov_b32_e32 v235, v159
	v_pk_mul_f32 v[148:149], v[124:125], v[150:151] op_sel_hi:[1,0]
	v_pk_mul_f32 v[146:147], v[122:123], v[150:151] op_sel_hi:[1,0]
	v_pk_mul_f32 v[156:157], v[128:129], v[150:151] op_sel_hi:[1,0]
	v_cvt_pk_bf16_f32 v146, v146, v147
	v_cvt_pk_bf16_f32 v147, v148, v149
	v_pk_mul_f32 v[148:149], v[126:127], v[150:151] op_sel_hi:[1,0]
	s_andn2_b64 vcc, exec, s[6:7]
	v_cvt_pk_bf16_f32 v148, v148, v149
	v_cvt_pk_bf16_f32 v149, v156, v157
	s_nop 1
	v_mov_b32_e32 v236, v146
	v_mov_b32_e32 v237, v147
	v_mov_b32_e32 v238, v148
	v_mov_b32_e32 v239, v149
	v_mov_b32_dpp v236, v232 row_shl:8 row_mask:0xf bank_mask:0x3
	v_mov_b32_dpp v237, v233 row_shl:8 row_mask:0xf bank_mask:0x3
	v_mov_b32_dpp v238, v234 row_shl:8 row_mask:0xf bank_mask:0x3
	v_mov_b32_dpp v239, v235 row_shl:8 row_mask:0xf bank_mask:0x3
	v_mov_b32_dpp v232, v146 row_shr:8 row_mask:0xf bank_mask:0xc
	v_mov_b32_dpp v233, v147 row_shr:8 row_mask:0xf bank_mask:0xc
	v_mov_b32_dpp v234, v148 row_shr:8 row_mask:0xf bank_mask:0xc
	v_mov_b32_dpp v235, v149 row_shr:8 row_mask:0xf bank_mask:0xc
	v_lshl_add_u64 v[240:241], v[160:161], 0, v[244:245]
	v_lshl_add_u64 v[242:243], v[160:161], 0, v[246:247]
	global_store_dwordx4 v[240:241], v[232:235], off
	global_store_dwordx4 v[242:243], v[236:239], off
	s_cbranch_vccnz .LBB0_204
	s_andn2_b64 vcc, exec, s[8:9]
	s_cbranch_vccnz .LBB0_190
	s_barrier
	s_branch .LBB0_190

; __global__ void __launch_bounds__(512, 2) mega_fwd(Params p) {
	.amdhsa_kernel _Z8mega_fwd6Params
		.amdhsa_group_segment_fixed_size 0
		.amdhsa_private_segment_fixed_size 0
		.amdhsa_kernarg_size 440
		.amdhsa_user_sgpr_count 2
		.amdhsa_user_sgpr_dispatch_ptr 0
		.amdhsa_user_sgpr_queue_ptr 0
		.amdhsa_user_sgpr_kernarg_segment_ptr 1
		.amdhsa_user_sgpr_dispatch_id 0
		.amdhsa_user_sgpr_kernarg_preload_length 0
		.amdhsa_user_sgpr_kernarg_preload_offset 0
		.amdhsa_user_sgpr_private_segment_size 0
		.amdhsa_uses_dynamic_stack 0
		.amdhsa_enable_private_segment 0
		.amdhsa_system_sgpr_workgroup_id_x 1
		.amdhsa_system_sgpr_workgroup_id_y 0
		.amdhsa_system_sgpr_workgroup_id_z 0
		.amdhsa_system_sgpr_workgroup_info 0
		.amdhsa_system_vgpr_workitem_id 0
		.amdhsa_next_free_vgpr 248
		.amdhsa_next_free_sgpr 102
		.amdhsa_accum_offset 248
		.amdhsa_reserve_vcc 1
		.amdhsa_float_round_mode_32 0
		.amdhsa_float_round_mode_16_64 0
		.amdhsa_float_denorm_mode_32 3
		.amdhsa_float_denorm_mode_16_64 3
		.amdhsa_dx10_clamp 1
		.amdhsa_ieee_mode 1
		.amdhsa_fp16_overflow 0
		.amdhsa_tg_split 0
		.amdhsa_exception_fp_ieee_invalid_op 0
		.amdhsa_exception_fp_denorm_src 0
		.amdhsa_exception_fp_ieee_div_zero 0
		.amdhsa_exception_fp_ieee_overflow 0
		.amdhsa_exception_fp_ieee_underflow 0
		.amdhsa_exception_fp_ieee_inexact 0
		.amdhsa_exception_int_div_zero 0
	.end_amdhsa_kernel

; __global__ void __launch_bounds__(512, 2) mega_fwd(Params p) {
amdhsa.kernels:
  - .agpr_count:     0
    .args:
      - .offset:         0
        .size:           184
        .value_kind:     by_value
      - .offset:         184
        .size:           4
        .value_kind:     hidden_block_count_x
      - .offset:         188
        .size:           4
        .value_kind:     hidden_block_count_y
      - .offset:         192
        .size:           4
        .value_kind:     hidden_block_count_z
      - .offset:         196
        .size:           2
        .value_kind:     hidden_group_size_x
      - .offset:         198
        .size:           2
        .value_kind:     hidden_group_size_y
      - .offset:         200
        .size:           2
        .value_kind:     hidden_group_size_z
      - .offset:         202
        .size:           2
        .value_kind:     hidden_remainder_x
      - .offset:         204
        .size:           2
        .value_kind:     hidden_remainder_y
      - .offset:         206
        .size:           2
        .value_kind:     hidden_remainder_z
      - .offset:         224
        .size:           8
        .value_kind:     hidden_global_offset_x
      - .offset:         232
        .size:           8
        .value_kind:     hidden_global_offset_y
      - .offset:         240
        .size:           8
        .value_kind:     hidden_global_offset_z
      - .offset:         248
        .size:           2
        .value_kind:     hidden_grid_dims
      - .offset:         304
        .size:           4
        .value_kind:     hidden_dynamic_lds_size
    .group_segment_fixed_size: 0
    .kernarg_segment_align: 8
    .kernarg_segment_size: 440
    .language:       OpenCL C
    .language_version:
      - 2
      - 0
    .max_flat_workgroup_size: 512
    .name:           _Z8mega_fwd6Params
    .private_segment_fixed_size: 0
    .sgpr_count:     108
    .sgpr_spill_count: 0
    .symbol:         _Z8mega_fwd6Params.kd
    .uniform_work_group_size: 1
    .uses_dynamic_stack: false
    .vgpr_count:     248
    .vgpr_spill_count: 0
    .wavefront_size: 64
